# SwiGLU epilogue: one reciprocal per element pair (1/d0 = d1*rcp(d0*d1), 1/d1 = d0*rcp(d0*d1)) instead of two
# baseline (speedup 1.0000x reference)
.Llast_0:
	v_add_u32_e32 v153, s64, v147
	ds_read_b128 v[160:163], v153
	v_xor_b32_e32 v253, 64, v153
	ds_read_b128 v[164:167], v253
	ds_read_b128 v[168:171], v153 offset:2048
	ds_read_b128 v[172:175], v253 offset:2048
	v_add_u32_e32 v153, s65, v147
	ds_read_b128 v[176:179], v153
	v_xor_b32_e32 v253, 64, v153
	ds_read_b128 v[180:183], v253
	ds_read_b128 v[186:189], v153 offset:2048
	ds_read_b128 v[190:193], v253 offset:2048
	s_add_u32 s48, s44, 0xfffc0080
	s_addc_u32 s49, s45, -1
	s_and_b64 s[46:47], s[46:47], exec
	s_cselect_b32 s49, s27, s49
	s_cselect_b32 s48, s68, s48
	s_cselect_b32 s47, s69, s74
	s_cselect_b32 s46, s70, s71
	v_lshl_add_u64 v[154:155], s[44:45], 0, v[138:139]
	s_add_i32 m0, s55, 0xc000
	ds_read_b128 v[194:197], v150
	v_xor_b32_e32 v253, 64, v150
	ds_read_b128 v[198:201], v253
	ds_read_b128 v[202:205], v150 offset:2048
	ds_read_b128 v[206:209], v253 offset:2048
	ds_read_b128 v[210:213], v150 offset:4096
	ds_read_b128 v[214:217], v253 offset:4096
	ds_read_b128 v[218:221], v150 offset:6144
	ds_read_b128 v[222:225], v253 offset:6144
	global_load_lds_dwordx4 v[154:155], off
	v_lshl_add_u64 v[154:155], s[44:45], 0, v[136:137]
	s_add_i32 m0, s55, 0xe000
	s_nop 0
	global_load_lds_dwordx4 v[154:155], off
	s_waitcnt vmcnt(8)
	s_waitcnt lgkmcnt(0)
	s_setprio 1
	s_barrier
	v_mfma_f32_16x16x32_bf16 v[124:127], v[160:163], v[194:197], v[124:127]
	v_mfma_f32_16x16x32_bf16 v[124:127], v[164:167], v[198:201], v[124:127]
	v_mfma_f32_16x16x32_bf16 v[116:119], v[172:175], v[198:201], v[116:119]
	v_mfma_f32_16x16x32_bf16 v[116:119], v[168:171], v[194:197], v[116:119]
	v_mfma_f32_16x16x32_bf16 v[100:103], v[168:171], v[202:205], v[100:103]
	v_mfma_f32_16x16x32_bf16 v[100:103], v[172:175], v[206:209], v[100:103]
	v_mfma_f32_16x16x32_bf16 v[108:111], v[164:167], v[206:209], v[108:111]
	v_mfma_f32_16x16x32_bf16 v[108:111], v[160:163], v[202:205], v[108:111]
	v_mfma_f32_16x16x32_bf16 v[92:95], v[160:163], v[210:213], v[92:95]
	v_mfma_f32_16x16x32_bf16 v[92:95], v[164:167], v[214:217], v[92:95]
	v_mfma_f32_16x16x32_bf16 v[84:87], v[172:175], v[214:217], v[84:87]
	v_mfma_f32_16x16x32_bf16 v[84:87], v[168:171], v[210:213], v[84:87]
	v_mfma_f32_16x16x32_bf16 v[68:71], v[168:171], v[218:221], v[68:71]
	v_mfma_f32_16x16x32_bf16 v[68:71], v[172:175], v[222:225], v[68:71]
	v_mfma_f32_16x16x32_bf16 v[76:79], v[164:167], v[222:225], v[76:79]
	v_mfma_f32_16x16x32_bf16 v[76:79], v[160:163], v[218:221], v[76:79]
	s_setprio 0
	s_setprio 1
	v_mfma_f32_16x16x32_bf16 v[120:123], v[176:179], v[194:197], v[120:123]
	v_mfma_f32_16x16x32_bf16 v[120:123], v[180:183], v[198:201], v[120:123]
	v_mfma_f32_16x16x32_bf16 v[112:115], v[190:193], v[198:201], v[112:115]
	v_mfma_f32_16x16x32_bf16 v[112:115], v[186:189], v[194:197], v[112:115]
	v_mfma_f32_16x16x32_bf16 v[96:99], v[186:189], v[202:205], v[96:99]
	v_mfma_f32_16x16x32_bf16 v[96:99], v[190:193], v[206:209], v[96:99]
	v_mfma_f32_16x16x32_bf16 v[104:107], v[180:183], v[206:209], v[104:107]
	v_mfma_f32_16x16x32_bf16 v[104:107], v[176:179], v[202:205], v[104:107]
	v_mfma_f32_16x16x32_bf16 v[88:91], v[176:179], v[210:213], v[88:91]
	v_mfma_f32_16x16x32_bf16 v[88:91], v[180:183], v[214:217], v[88:91]
	v_mfma_f32_16x16x32_bf16 v[80:83], v[190:193], v[214:217], v[80:83]
	v_mfma_f32_16x16x32_bf16 v[80:83], v[186:189], v[210:213], v[80:83]
	v_mfma_f32_16x16x32_bf16 v[64:67], v[186:189], v[218:221], v[64:67]
	v_mfma_f32_16x16x32_bf16 v[64:67], v[190:193], v[222:225], v[64:67]
	v_mfma_f32_16x16x32_bf16 v[72:75], v[180:183], v[222:225], v[72:75]
	v_mfma_f32_16x16x32_bf16 v[72:75], v[176:179], v[218:221], v[72:75]
	s_barrier
	s_setprio 0
	s_add_i32 s76, s64, s52
	v_lshl_add_u64 v[154:155], s[46:47], 0, v[132:133]
	s_mov_b32 m0, s76
	ds_read_b128 v[194:197], v150 offset:16384
	v_xor_b32_e32 v253, 64, v150
	ds_read_b128 v[198:201], v253 offset:16384
	ds_read_b128 v[202:205], v150 offset:18432
	ds_read_b128 v[206:209], v253 offset:18432
	ds_read_b128 v[210:213], v150 offset:20480
	ds_read_b128 v[214:217], v253 offset:20480
	ds_read_b128 v[218:221], v150 offset:22528
	ds_read_b128 v[222:225], v253 offset:22528
	global_load_lds_dwordx4 v[154:155], off
	s_add_i32 m0, s76, 0x2000
	s_add_u32 s76, s46, 0x40000
	v_lshl_add_u64 v[226:227], s[46:47], 0, v[128:129]
	s_addc_u32 s77, s47, 0
	s_add_i32 s78, s65, s52
	global_load_lds_dwordx4 v[226:227], off
	v_lshl_add_u64 v[228:229], s[76:77], 0, v[132:133]
	s_mov_b32 m0, s78
	v_lshl_add_u64 v[230:231], s[48:49], 0, v[130:131]
	global_load_lds_dwordx4 v[228:229], off
	v_lshl_add_u64 v[228:229], s[76:77], 0, v[128:129]
	s_add_i32 m0, s78, 0x2000
	s_nop 0
	global_load_lds_dwordx4 v[228:229], off
	v_lshl_add_u64 v[228:229], s[48:49], 0, v[134:135]
	s_mov_b32 m0, s55
	s_nop 0
	global_load_lds_dwordx4 v[228:229], off
	s_mov_b32 m0, s56
	s_nop 0
	global_load_lds_dwordx4 v[230:231], off
	s_waitcnt vmcnt(8)
	s_waitcnt lgkmcnt(0)
	s_setprio 1
	s_barrier
	v_mfma_f32_16x16x32_bf16 v[60:63], v[160:163], v[194:197], v[60:63]
	v_mfma_f32_16x16x32_bf16 v[60:63], v[164:167], v[198:201], v[60:63]
	v_mfma_f32_16x16x32_bf16 v[52:55], v[172:175], v[198:201], v[52:55]
	v_mfma_f32_16x16x32_bf16 v[52:55], v[168:171], v[194:197], v[52:55]
	v_mfma_f32_16x16x32_bf16 v[36:39], v[168:171], v[202:205], v[36:39]
	v_mfma_f32_16x16x32_bf16 v[36:39], v[172:175], v[206:209], v[36:39]
	v_mfma_f32_16x16x32_bf16 v[44:47], v[164:167], v[206:209], v[44:47]
	v_mfma_f32_16x16x32_bf16 v[44:47], v[160:163], v[202:205], v[44:47]
	v_mfma_f32_16x16x32_bf16 v[28:31], v[160:163], v[210:213], v[28:31]
	v_mfma_f32_16x16x32_bf16 v[28:31], v[164:167], v[214:217], v[28:31]
	v_mfma_f32_16x16x32_bf16 v[20:23], v[172:175], v[214:217], v[20:23]
	v_mfma_f32_16x16x32_bf16 v[20:23], v[168:171], v[210:213], v[20:23]
	v_mfma_f32_16x16x32_bf16 v[4:7], v[168:171], v[218:221], v[4:7]
	v_mfma_f32_16x16x32_bf16 v[4:7], v[172:175], v[222:225], v[4:7]
	v_mfma_f32_16x16x32_bf16 v[12:15], v[164:167], v[222:225], v[12:15]
	v_mfma_f32_16x16x32_bf16 v[12:15], v[160:163], v[218:221], v[12:15]
	s_setprio 0
	s_setprio 1
	v_mfma_f32_16x16x32_bf16 v[56:59], v[176:179], v[194:197], v[56:59]
	v_mfma_f32_16x16x32_bf16 v[56:59], v[180:183], v[198:201], v[56:59]
	v_mfma_f32_16x16x32_bf16 v[48:51], v[190:193], v[198:201], v[48:51]
	v_mfma_f32_16x16x32_bf16 v[48:51], v[186:189], v[194:197], v[48:51]
	v_mfma_f32_16x16x32_bf16 v[32:35], v[186:189], v[202:205], v[32:35]
	v_mfma_f32_16x16x32_bf16 v[32:35], v[190:193], v[206:209], v[32:35]
	v_mfma_f32_16x16x32_bf16 v[40:43], v[180:183], v[206:209], v[40:43]
	v_mfma_f32_16x16x32_bf16 v[40:43], v[176:179], v[202:205], v[40:43]
	v_mfma_f32_16x16x32_bf16 v[24:27], v[176:179], v[210:213], v[24:27]
	v_mfma_f32_16x16x32_bf16 v[24:27], v[180:183], v[214:217], v[24:27]
	v_mfma_f32_16x16x32_bf16 v[16:19], v[190:193], v[214:217], v[16:19]
	v_mfma_f32_16x16x32_bf16 v[16:19], v[186:189], v[210:213], v[16:19]
	v_mfma_f32_16x16x32_bf16 v[0:3], v[186:189], v[218:221], v[0:3]
	v_mfma_f32_16x16x32_bf16 v[0:3], v[190:193], v[222:225], v[0:3]
	v_mfma_f32_16x16x32_bf16 v[8:11], v[180:183], v[222:225], v[8:11]
	v_mfma_f32_16x16x32_bf16 v[8:11], v[176:179], v[218:221], v[8:11]
	s_barrier
	s_setprio 0
	s_add_i32 s76, 0, 0x18000
	v_add_u32_e32 v153, s76, v147
	s_add_i32 s77, 0, 0x1c000
	ds_read_b128 v[160:163], v153
	v_xor_b32_e32 v253, 64, v153
	ds_read_b128 v[164:167], v253
	ds_read_b128 v[168:171], v153 offset:2048
	ds_read_b128 v[172:175], v253 offset:2048
	v_add_u32_e32 v153, s77, v147
	ds_read_b128 v[176:179], v153
	v_xor_b32_e32 v253, 64, v153
	ds_read_b128 v[180:183], v253
	ds_read_b128 v[186:189], v153 offset:2048
	ds_read_b128 v[190:193], v253 offset:2048
	s_add_u32 s48, s48, 0x40000
	s_addc_u32 s49, s49, 0
	s_mov_b32 m0, s57
	v_lshl_add_u64 v[232:233], s[48:49], 0, v[134:135]
	ds_read_b128 v[194:197], v150 offset:32768
	v_xor_b32_e32 v253, 64, v150
	ds_read_b128 v[198:201], v253 offset:32768
	ds_read_b128 v[202:205], v150 offset:34816
	ds_read_b128 v[206:209], v253 offset:34816
	ds_read_b128 v[210:213], v150 offset:36864
	ds_read_b128 v[214:217], v253 offset:36864
	ds_read_b128 v[218:221], v150 offset:38912
	ds_read_b128 v[222:225], v253 offset:38912
	global_load_lds_dwordx4 v[232:233], off
	v_lshl_add_u64 v[232:233], s[48:49], 0, v[130:131]
	s_mov_b32 m0, s58
	s_nop 0
	global_load_lds_dwordx4 v[232:233], off
	s_waitcnt vmcnt(8)
	s_waitcnt lgkmcnt(0)
	s_setprio 1
	s_barrier
	v_mfma_f32_16x16x32_bf16 v[124:127], v[160:163], v[194:197], v[124:127]
	v_mfma_f32_16x16x32_bf16 v[124:127], v[164:167], v[198:201], v[124:127]
	v_mfma_f32_16x16x32_bf16 v[116:119], v[172:175], v[198:201], v[116:119]
	v_mfma_f32_16x16x32_bf16 v[116:119], v[168:171], v[194:197], v[116:119]
	v_mfma_f32_16x16x32_bf16 v[100:103], v[168:171], v[202:205], v[100:103]
	v_mfma_f32_16x16x32_bf16 v[100:103], v[172:175], v[206:209], v[100:103]
	v_mfma_f32_16x16x32_bf16 v[108:111], v[164:167], v[206:209], v[108:111]
	v_mfma_f32_16x16x32_bf16 v[108:111], v[160:163], v[202:205], v[108:111]
	v_mfma_f32_16x16x32_bf16 v[92:95], v[160:163], v[210:213], v[92:95]
	v_mfma_f32_16x16x32_bf16 v[92:95], v[164:167], v[214:217], v[92:95]
	v_mfma_f32_16x16x32_bf16 v[84:87], v[172:175], v[214:217], v[84:87]
	v_mfma_f32_16x16x32_bf16 v[84:87], v[168:171], v[210:213], v[84:87]
	v_mfma_f32_16x16x32_bf16 v[68:71], v[168:171], v[218:221], v[68:71]
	v_mfma_f32_16x16x32_bf16 v[68:71], v[172:175], v[222:225], v[68:71]
	v_mfma_f32_16x16x32_bf16 v[76:79], v[164:167], v[222:225], v[76:79]
	v_mfma_f32_16x16x32_bf16 v[76:79], v[160:163], v[218:221], v[76:79]
	s_setprio 0
	s_setprio 1
	v_mfma_f32_16x16x32_bf16 v[120:123], v[176:179], v[194:197], v[120:123]
	v_mfma_f32_16x16x32_bf16 v[120:123], v[180:183], v[198:201], v[120:123]
	v_mfma_f32_16x16x32_bf16 v[112:115], v[190:193], v[198:201], v[112:115]
	v_mfma_f32_16x16x32_bf16 v[112:115], v[186:189], v[194:197], v[112:115]
	v_mfma_f32_16x16x32_bf16 v[96:99], v[186:189], v[202:205], v[96:99]
	v_mfma_f32_16x16x32_bf16 v[96:99], v[190:193], v[206:209], v[96:99]
	v_mfma_f32_16x16x32_bf16 v[104:107], v[180:183], v[206:209], v[104:107]
	v_mfma_f32_16x16x32_bf16 v[104:107], v[176:179], v[202:205], v[104:107]
	v_mfma_f32_16x16x32_bf16 v[88:91], v[176:179], v[210:213], v[88:91]
	v_mfma_f32_16x16x32_bf16 v[88:91], v[180:183], v[214:217], v[88:91]
	v_mfma_f32_16x16x32_bf16 v[80:83], v[190:193], v[214:217], v[80:83]
	v_mfma_f32_16x16x32_bf16 v[80:83], v[186:189], v[210:213], v[80:83]
	v_mfma_f32_16x16x32_bf16 v[64:67], v[186:189], v[218:221], v[64:67]
	v_mfma_f32_16x16x32_bf16 v[64:67], v[190:193], v[222:225], v[64:67]
	v_mfma_f32_16x16x32_bf16 v[72:75], v[180:183], v[222:225], v[72:75]
	v_mfma_f32_16x16x32_bf16 v[72:75], v[176:179], v[218:221], v[72:75]
	s_barrier
	s_setprio 0
	v_add_u32_e32 v234, 0x21000, v151
	ds_read_b128 v[236:239], v234
	ds_read_b128 v[240:243], v234 offset:256
	ds_read_b128 v[244:247], v234 offset:512
	ds_read_b128 v[248:251], v234 offset:768
	v_add_u32_e32 v235, s23, v146
	v_mul_u32_u24_e32 v235, 0x1600, v235
	v_lshl_or_b32 v234, s67, 7, v149
	v_lshl_add_u32 v235, v234, 1, v235
	s_add_i32 s48, s76, s52
	v_lshl_add_u64 v[154:155], v[154:155], 0, s[14:15]
	s_mov_b32 m0, s48
	ds_read_b128 v[194:197], v150 offset:49152
	v_xor_b32_e32 v253, 64, v150
	ds_read_b128 v[198:201], v253 offset:49152
	ds_read_b128 v[202:205], v150 offset:51200
	ds_read_b128 v[206:209], v253 offset:51200
	ds_read_b128 v[210:213], v150 offset:53248
	ds_read_b128 v[214:217], v253 offset:53248
	ds_read_b128 v[218:221], v150 offset:55296
	ds_read_b128 v[222:225], v253 offset:55296
	global_load_lds_dwordx4 v[154:155], off
	s_add_i32 m0, s48, 0x2000
	s_add_u32 s46, s46, 0x40080
	v_lshl_add_u64 v[154:155], v[226:227], 0, s[14:15]
	s_addc_u32 s47, s47, 0
	s_add_i32 s48, s77, s52
	global_load_lds_dwordx4 v[154:155], off
	v_lshl_add_u64 v[154:155], s[46:47], 0, v[132:133]
	s_mov_b32 m0, s48
	s_nop 0
	global_load_lds_dwordx4 v[154:155], off
	v_lshl_add_u64 v[154:155], s[46:47], 0, v[128:129]
	s_add_i32 m0, s48, 0x2000
	s_nop 0
	global_load_lds_dwordx4 v[154:155], off
	v_lshl_add_u64 v[154:155], v[228:229], 0, s[14:15]
	s_mov_b32 m0, s60
	s_nop 0
	global_load_lds_dwordx4 v[154:155], off
	v_lshl_add_u64 v[154:155], v[230:231], 0, s[14:15]
	s_mov_b32 m0, s61
	s_nop 0
	global_load_lds_dwordx4 v[154:155], off
	s_waitcnt lgkmcnt(8)
	v_add_f32_e32 v236, v236, v237
	v_add_f32_e32 v238, v238, v239
	v_add_f32_e32 v240, v240, v241
	v_add_f32_e32 v242, v242, v243
	v_add_f32_e32 v244, v244, v245
	v_add_f32_e32 v246, v246, v247
	v_add_f32_e32 v248, v248, v249
	v_add_f32_e32 v250, v250, v251
	v_add_f32_e32 v236, v236, v238
	v_add_f32_e32 v240, v240, v242
	v_add_f32_e32 v244, v244, v246
	v_add_f32_e32 v248, v248, v250
	v_fmamk_f32 v236, v236, 0x3a800000, v152
	v_fmamk_f32 v240, v240, 0x3a800000, v152
	v_fmamk_f32 v244, v244, 0x3a800000, v152
	v_fmamk_f32 v248, v248, 0x3a800000, v152
	v_rsq_f32_e32 v236, v236
	v_rsq_f32_e32 v240, v240
	v_rsq_f32_e32 v244, v244
	v_rsq_f32_e32 v248, v248
	v_mul_f32_e32 v252, 0xbfb8aa3b, v236
	v_mul_f32_e32 v254, v236, v236
	v_rcp_f32_e32 v254, v254
	v_pk_mul_f32 v[120:121], v[124:125], v[120:121]
	v_pk_mul_f32 v[122:123], v[126:127], v[122:123]
	v_pk_mul_f32 v[112:113], v[116:117], v[112:113]
	v_pk_mul_f32 v[114:115], v[118:119], v[114:115]
	v_pk_mul_f32 v[124:125], v[124:125], v[252:253] op_sel_hi:[1,0]
	v_pk_mul_f32 v[126:127], v[126:127], v[252:253] op_sel_hi:[1,0]
	v_pk_mul_f32 v[116:117], v[116:117], v[252:253] op_sel_hi:[1,0]
	v_pk_mul_f32 v[118:119], v[118:119], v[252:253] op_sel_hi:[1,0]
	v_exp_f32_e32 v124, v124
	v_exp_f32_e32 v125, v125
	v_exp_f32_e32 v126, v126
	v_exp_f32_e32 v127, v127
	v_exp_f32_e32 v116, v116
	v_exp_f32_e32 v117, v117
	v_exp_f32_e32 v118, v118
	v_exp_f32_e32 v119, v119
	v_pk_fma_f32 v[124:125], v[124:125], v[254:255], v[254:255] op_sel_hi:[1,0,0]
	v_pk_fma_f32 v[126:127], v[126:127], v[254:255], v[254:255] op_sel_hi:[1,0,0]
	v_pk_fma_f32 v[116:117], v[116:117], v[254:255], v[254:255] op_sel_hi:[1,0,0]
	v_pk_fma_f32 v[118:119], v[118:119], v[254:255], v[254:255] op_sel_hi:[1,0,0]
	v_mul_f32_e32 v238, v124, v125
	v_mul_f32_e32 v242, v126, v127
	v_mul_f32_e32 v246, v116, v117
	v_mul_f32_e32 v250, v118, v119
	v_rcp_f32_e32 v238, v238
	v_rcp_f32_e32 v242, v242
	v_rcp_f32_e32 v246, v246
	v_rcp_f32_e32 v250, v250
	v_pk_mul_f32 v[124:125], v[124:125], v[238:239] op_sel:[1,0] op_sel_hi:[0,0]
	v_pk_mul_f32 v[126:127], v[126:127], v[242:243] op_sel:[1,0] op_sel_hi:[0,0]
	v_pk_mul_f32 v[116:117], v[116:117], v[246:247] op_sel:[1,0] op_sel_hi:[0,0]
	v_pk_mul_f32 v[118:119], v[118:119], v[250:251] op_sel:[1,0] op_sel_hi:[0,0]
	v_pk_mul_f32 v[120:121], v[120:121], v[124:125]
	v_pk_mul_f32 v[122:123], v[122:123], v[126:127]
	v_pk_mul_f32 v[112:113], v[112:113], v[116:117]
	v_pk_mul_f32 v[114:115], v[114:115], v[118:119]
	v_cvt_pk_bf16_f32 v120, v120, v121
	v_cvt_pk_bf16_f32 v121, v122, v123
	v_cvt_pk_bf16_f32 v122, v112, v113
	v_cvt_pk_bf16_f32 v123, v114, v115
	global_store_dwordx4 v235, v[120:123], s[10:11]
	v_add_u32_e32 v234, 0x16000, v235
	v_mul_f32_e32 v252, 0xbfb8aa3b, v240
	v_mul_f32_e32 v254, v240, v240
	v_rcp_f32_e32 v254, v254
	v_pk_mul_f32 v[104:105], v[108:109], v[104:105]
	v_pk_mul_f32 v[106:107], v[110:111], v[106:107]
	v_pk_mul_f32 v[96:97], v[100:101], v[96:97]
	v_pk_mul_f32 v[98:99], v[102:103], v[98:99]
	v_pk_mul_f32 v[108:109], v[108:109], v[252:253] op_sel_hi:[1,0]
	v_pk_mul_f32 v[110:111], v[110:111], v[252:253] op_sel_hi:[1,0]
	v_pk_mul_f32 v[100:101], v[100:101], v[252:253] op_sel_hi:[1,0]
	v_pk_mul_f32 v[102:103], v[102:103], v[252:253] op_sel_hi:[1,0]
	v_exp_f32_e32 v108, v108
	v_exp_f32_e32 v109, v109
	v_exp_f32_e32 v110, v110
	v_exp_f32_e32 v111, v111
	v_exp_f32_e32 v100, v100
	v_exp_f32_e32 v101, v101
	v_exp_f32_e32 v102, v102
	v_exp_f32_e32 v103, v103
	v_pk_fma_f32 v[108:109], v[108:109], v[254:255], v[254:255] op_sel_hi:[1,0,0]
	v_pk_fma_f32 v[110:111], v[110:111], v[254:255], v[254:255] op_sel_hi:[1,0,0]
	v_pk_fma_f32 v[100:101], v[100:101], v[254:255], v[254:255] op_sel_hi:[1,0,0]
	v_pk_fma_f32 v[102:103], v[102:103], v[254:255], v[254:255] op_sel_hi:[1,0,0]
	v_mul_f32_e32 v238, v108, v109
	v_mul_f32_e32 v242, v110, v111
	v_mul_f32_e32 v246, v100, v101
	v_mul_f32_e32 v250, v102, v103
	v_rcp_f32_e32 v238, v238
	v_rcp_f32_e32 v242, v242
	v_rcp_f32_e32 v246, v246
	v_rcp_f32_e32 v250, v250
	v_pk_mul_f32 v[108:109], v[108:109], v[238:239] op_sel:[1,0] op_sel_hi:[0,0]
	v_pk_mul_f32 v[110:111], v[110:111], v[242:243] op_sel:[1,0] op_sel_hi:[0,0]
	v_pk_mul_f32 v[100:101], v[100:101], v[246:247] op_sel:[1,0] op_sel_hi:[0,0]
	v_pk_mul_f32 v[102:103], v[102:103], v[250:251] op_sel:[1,0] op_sel_hi:[0,0]
	v_pk_mul_f32 v[104:105], v[104:105], v[108:109]
	v_pk_mul_f32 v[106:107], v[106:107], v[110:111]
	v_pk_mul_f32 v[96:97], v[96:97], v[100:101]
	v_pk_mul_f32 v[98:99], v[98:99], v[102:103]
	v_cvt_pk_bf16_f32 v104, v104, v105
	v_cvt_pk_bf16_f32 v105, v106, v107
	v_cvt_pk_bf16_f32 v106, v96, v97
	v_cvt_pk_bf16_f32 v107, v98, v99
	global_store_dwordx4 v234, v[104:107], s[10:11]
	v_add_u32_e32 v235, 0x16000, v234
	v_mul_f32_e32 v252, 0xbfb8aa3b, v244
	v_mul_f32_e32 v254, v244, v244
	v_rcp_f32_e32 v254, v254
	v_pk_mul_f32 v[88:89], v[92:93], v[88:89]
	v_pk_mul_f32 v[90:91], v[94:95], v[90:91]
	v_pk_mul_f32 v[80:81], v[84:85], v[80:81]
	v_pk_mul_f32 v[82:83], v[86:87], v[82:83]
	v_pk_mul_f32 v[92:93], v[92:93], v[252:253] op_sel_hi:[1,0]
	v_pk_mul_f32 v[94:95], v[94:95], v[252:253] op_sel_hi:[1,0]
	v_pk_mul_f32 v[84:85], v[84:85], v[252:253] op_sel_hi:[1,0]
	v_pk_mul_f32 v[86:87], v[86:87], v[252:253] op_sel_hi:[1,0]
	v_exp_f32_e32 v92, v92
	v_exp_f32_e32 v93, v93
	v_exp_f32_e32 v94, v94
	v_exp_f32_e32 v95, v95
	v_exp_f32_e32 v84, v84
	v_exp_f32_e32 v85, v85
	v_exp_f32_e32 v86, v86
	v_exp_f32_e32 v87, v87
	v_pk_fma_f32 v[92:93], v[92:93], v[254:255], v[254:255] op_sel_hi:[1,0,0]
	v_pk_fma_f32 v[94:95], v[94:95], v[254:255], v[254:255] op_sel_hi:[1,0,0]
	v_pk_fma_f32 v[84:85], v[84:85], v[254:255], v[254:255] op_sel_hi:[1,0,0]
	v_pk_fma_f32 v[86:87], v[86:87], v[254:255], v[254:255] op_sel_hi:[1,0,0]
	v_mul_f32_e32 v238, v92, v93
	v_mul_f32_e32 v242, v94, v95
	v_mul_f32_e32 v246, v84, v85
	v_mul_f32_e32 v250, v86, v87
	v_rcp_f32_e32 v238, v238
	v_rcp_f32_e32 v242, v242
	v_rcp_f32_e32 v246, v246
	v_rcp_f32_e32 v250, v250
	v_pk_mul_f32 v[92:93], v[92:93], v[238:239] op_sel:[1,0] op_sel_hi:[0,0]
	v_pk_mul_f32 v[94:95], v[94:95], v[242:243] op_sel:[1,0] op_sel_hi:[0,0]
	v_pk_mul_f32 v[84:85], v[84:85], v[246:247] op_sel:[1,0] op_sel_hi:[0,0]
	v_pk_mul_f32 v[86:87], v[86:87], v[250:251] op_sel:[1,0] op_sel_hi:[0,0]
	v_pk_mul_f32 v[88:89], v[88:89], v[92:93]
	v_pk_mul_f32 v[90:91], v[90:91], v[94:95]
	v_pk_mul_f32 v[80:81], v[80:81], v[84:85]
	v_pk_mul_f32 v[82:83], v[82:83], v[86:87]
	v_cvt_pk_bf16_f32 v88, v88, v89
	v_cvt_pk_bf16_f32 v89, v90, v91
	v_cvt_pk_bf16_f32 v90, v80, v81
	v_cvt_pk_bf16_f32 v91, v82, v83
	global_store_dwordx4 v235, v[88:91], s[10:11]
	v_add_u32_e32 v234, 0x16000, v235
	v_mul_f32_e32 v252, 0xbfb8aa3b, v248
	v_mul_f32_e32 v254, v248, v248
	v_rcp_f32_e32 v254, v254
	v_pk_mul_f32 v[72:73], v[76:77], v[72:73]
	v_pk_mul_f32 v[74:75], v[78:79], v[74:75]
	v_pk_mul_f32 v[64:65], v[68:69], v[64:65]
	v_pk_mul_f32 v[66:67], v[70:71], v[66:67]
	v_pk_mul_f32 v[76:77], v[76:77], v[252:253] op_sel_hi:[1,0]
	v_pk_mul_f32 v[78:79], v[78:79], v[252:253] op_sel_hi:[1,0]
	v_pk_mul_f32 v[68:69], v[68:69], v[252:253] op_sel_hi:[1,0]
	v_pk_mul_f32 v[70:71], v[70:71], v[252:253] op_sel_hi:[1,0]
	v_exp_f32_e32 v76, v76
	v_exp_f32_e32 v77, v77
	v_exp_f32_e32 v78, v78
	v_exp_f32_e32 v79, v79
	v_exp_f32_e32 v68, v68
	v_exp_f32_e32 v69, v69
	v_exp_f32_e32 v70, v70
	v_exp_f32_e32 v71, v71
	v_pk_fma_f32 v[76:77], v[76:77], v[254:255], v[254:255] op_sel_hi:[1,0,0]
	v_pk_fma_f32 v[78:79], v[78:79], v[254:255], v[254:255] op_sel_hi:[1,0,0]
	v_pk_fma_f32 v[68:69], v[68:69], v[254:255], v[254:255] op_sel_hi:[1,0,0]
	v_pk_fma_f32 v[70:71], v[70:71], v[254:255], v[254:255] op_sel_hi:[1,0,0]
	v_mul_f32_e32 v238, v76, v77
	v_mul_f32_e32 v242, v78, v79
	v_mul_f32_e32 v246, v68, v69
	v_mul_f32_e32 v250, v70, v71
	v_rcp_f32_e32 v238, v238
	v_rcp_f32_e32 v242, v242
	v_rcp_f32_e32 v246, v246
	v_rcp_f32_e32 v250, v250
	v_pk_mul_f32 v[76:77], v[76:77], v[238:239] op_sel:[1,0] op_sel_hi:[0,0]
	v_pk_mul_f32 v[78:79], v[78:79], v[242:243] op_sel:[1,0] op_sel_hi:[0,0]
	v_pk_mul_f32 v[68:69], v[68:69], v[246:247] op_sel:[1,0] op_sel_hi:[0,0]
	v_pk_mul_f32 v[70:71], v[70:71], v[250:251] op_sel:[1,0] op_sel_hi:[0,0]
	v_pk_mul_f32 v[72:73], v[72:73], v[76:77]
	v_pk_mul_f32 v[74:75], v[74:75], v[78:79]
	v_pk_mul_f32 v[64:65], v[64:65], v[68:69]
	v_pk_mul_f32 v[66:67], v[66:67], v[70:71]
	v_cvt_pk_bf16_f32 v72, v72, v73
	v_cvt_pk_bf16_f32 v73, v74, v75
	v_cvt_pk_bf16_f32 v74, v64, v65
	v_cvt_pk_bf16_f32 v75, v66, v67
	global_store_dwordx4 v234, v[72:75], s[10:11]
	s_waitcnt vmcnt(12)
	s_waitcnt lgkmcnt(0)
	s_setprio 1
	s_barrier
	v_mfma_f32_16x16x32_bf16 v[60:63], v[160:163], v[194:197], v[60:63]
	v_mfma_f32_16x16x32_bf16 v[60:63], v[164:167], v[198:201], v[60:63]
	v_mfma_f32_16x16x32_bf16 v[52:55], v[172:175], v[198:201], v[52:55]
	v_mfma_f32_16x16x32_bf16 v[52:55], v[168:171], v[194:197], v[52:55]
	v_mfma_f32_16x16x32_bf16 v[36:39], v[168:171], v[202:205], v[36:39]
	v_mfma_f32_16x16x32_bf16 v[36:39], v[172:175], v[206:209], v[36:39]
	v_mfma_f32_16x16x32_bf16 v[44:47], v[164:167], v[206:209], v[44:47]
	v_mfma_f32_16x16x32_bf16 v[44:47], v[160:163], v[202:205], v[44:47]
	v_mfma_f32_16x16x32_bf16 v[28:31], v[160:163], v[210:213], v[28:31]
	v_mfma_f32_16x16x32_bf16 v[28:31], v[164:167], v[214:217], v[28:31]
	v_mfma_f32_16x16x32_bf16 v[20:23], v[172:175], v[214:217], v[20:23]
	v_mfma_f32_16x16x32_bf16 v[20:23], v[168:171], v[210:213], v[20:23]
	v_mfma_f32_16x16x32_bf16 v[4:7], v[168:171], v[218:221], v[4:7]
	v_mfma_f32_16x16x32_bf16 v[4:7], v[172:175], v[222:225], v[4:7]
	v_mfma_f32_16x16x32_bf16 v[12:15], v[164:167], v[222:225], v[12:15]
	v_mfma_f32_16x16x32_bf16 v[12:15], v[160:163], v[218:221], v[12:15]
	s_setprio 0
	s_setprio 1
	v_mfma_f32_16x16x32_bf16 v[56:59], v[176:179], v[194:197], v[56:59]
	v_mfma_f32_16x16x32_bf16 v[56:59], v[180:183], v[198:201], v[56:59]
	v_mfma_f32_16x16x32_bf16 v[48:51], v[190:193], v[198:201], v[48:51]
	v_mfma_f32_16x16x32_bf16 v[48:51], v[186:189], v[194:197], v[48:51]
	v_mfma_f32_16x16x32_bf16 v[32:35], v[186:189], v[202:205], v[32:35]
	v_mfma_f32_16x16x32_bf16 v[32:35], v[190:193], v[206:209], v[32:35]
	v_mfma_f32_16x16x32_bf16 v[40:43], v[180:183], v[206:209], v[40:43]
	v_mfma_f32_16x16x32_bf16 v[40:43], v[176:179], v[202:205], v[40:43]
	v_mfma_f32_16x16x32_bf16 v[24:27], v[176:179], v[210:213], v[24:27]
	v_mfma_f32_16x16x32_bf16 v[24:27], v[180:183], v[214:217], v[24:27]
	v_mfma_f32_16x16x32_bf16 v[16:19], v[190:193], v[214:217], v[16:19]
	v_mfma_f32_16x16x32_bf16 v[16:19], v[186:189], v[210:213], v[16:19]
	v_mfma_f32_16x16x32_bf16 v[0:3], v[186:189], v[218:221], v[0:3]
	v_mfma_f32_16x16x32_bf16 v[0:3], v[190:193], v[222:225], v[0:3]
	v_mfma_f32_16x16x32_bf16 v[8:11], v[180:183], v[222:225], v[8:11]
	v_mfma_f32_16x16x32_bf16 v[8:11], v[176:179], v[218:221], v[8:11]
	s_barrier
	s_setprio 0
	s_add_i32 s75, s75, 2
	s_add_u32 s71, s71, 0x100
	s_addc_u32 s74, s74, 0
	s_add_u32 s44, s44, 0x100
	s_addc_u32 s45, s45, 0

.LBB0_80:
	v_add_u32_e32 v235, 0x84000, v235
	v_add_u32_e32 v234, 0x21800, v151
	ds_read_b128 v[236:239], v234
	ds_read_b128 v[240:243], v234 offset:256
	ds_read_b128 v[244:247], v234 offset:512
	ds_read_b128 v[248:251], v234 offset:768
	s_waitcnt lgkmcnt(0)
	v_add_f32_e32 v236, v236, v237
	v_add_f32_e32 v238, v238, v239
	v_add_f32_e32 v240, v240, v241
	v_add_f32_e32 v242, v242, v243
	v_add_f32_e32 v244, v244, v245
	v_add_f32_e32 v246, v246, v247
	v_add_f32_e32 v248, v248, v249
	v_add_f32_e32 v250, v250, v251
	v_add_f32_e32 v236, v236, v238
	v_add_f32_e32 v240, v240, v242
	v_add_f32_e32 v244, v244, v246
	v_add_f32_e32 v248, v248, v250
	v_fmamk_f32 v236, v236, 0x3a800000, v152
	v_fmamk_f32 v240, v240, 0x3a800000, v152
	v_fmamk_f32 v244, v244, 0x3a800000, v152
	v_fmamk_f32 v248, v248, 0x3a800000, v152
	v_rsq_f32_e32 v236, v236
	v_rsq_f32_e32 v240, v240
	v_rsq_f32_e32 v244, v244
	v_rsq_f32_e32 v248, v248
	v_mul_f32_e32 v252, 0xbfb8aa3b, v236
	v_mul_f32_e32 v254, v236, v236
	v_rcp_f32_e32 v254, v254
	v_pk_mul_f32 v[56:57], v[60:61], v[56:57]
	v_pk_mul_f32 v[58:59], v[62:63], v[58:59]
	v_pk_mul_f32 v[48:49], v[52:53], v[48:49]
	v_pk_mul_f32 v[50:51], v[54:55], v[50:51]
	v_pk_mul_f32 v[60:61], v[60:61], v[252:253] op_sel_hi:[1,0]
	v_pk_mul_f32 v[62:63], v[62:63], v[252:253] op_sel_hi:[1,0]
	v_pk_mul_f32 v[52:53], v[52:53], v[252:253] op_sel_hi:[1,0]
	v_pk_mul_f32 v[54:55], v[54:55], v[252:253] op_sel_hi:[1,0]
	v_exp_f32_e32 v60, v60
	v_exp_f32_e32 v61, v61
	v_exp_f32_e32 v62, v62
	v_exp_f32_e32 v63, v63
	v_exp_f32_e32 v52, v52
	v_exp_f32_e32 v53, v53
	v_exp_f32_e32 v54, v54
	v_exp_f32_e32 v55, v55
	v_pk_fma_f32 v[60:61], v[60:61], v[254:255], v[254:255] op_sel_hi:[1,0,0]
	v_pk_fma_f32 v[62:63], v[62:63], v[254:255], v[254:255] op_sel_hi:[1,0,0]
	v_pk_fma_f32 v[52:53], v[52:53], v[254:255], v[254:255] op_sel_hi:[1,0,0]
	v_pk_fma_f32 v[54:55], v[54:55], v[254:255], v[254:255] op_sel_hi:[1,0,0]
	v_mul_f32_e32 v238, v60, v61
	v_mul_f32_e32 v242, v62, v63
	v_mul_f32_e32 v246, v52, v53
	v_mul_f32_e32 v250, v54, v55
	v_rcp_f32_e32 v238, v238
	v_rcp_f32_e32 v242, v242
	v_rcp_f32_e32 v246, v246
	v_rcp_f32_e32 v250, v250
	v_pk_mul_f32 v[60:61], v[60:61], v[238:239] op_sel:[1,0] op_sel_hi:[0,0]
	v_pk_mul_f32 v[62:63], v[62:63], v[242:243] op_sel:[1,0] op_sel_hi:[0,0]
	v_pk_mul_f32 v[52:53], v[52:53], v[246:247] op_sel:[1,0] op_sel_hi:[0,0]
	v_pk_mul_f32 v[54:55], v[54:55], v[250:251] op_sel:[1,0] op_sel_hi:[0,0]
	v_pk_mul_f32 v[56:57], v[56:57], v[60:61]
	v_pk_mul_f32 v[58:59], v[58:59], v[62:63]
	v_pk_mul_f32 v[48:49], v[48:49], v[52:53]
	v_pk_mul_f32 v[50:51], v[50:51], v[54:55]
	v_cvt_pk_bf16_f32 v56, v56, v57
	v_cvt_pk_bf16_f32 v57, v58, v59
	v_cvt_pk_bf16_f32 v58, v48, v49
	v_cvt_pk_bf16_f32 v59, v50, v51
	global_store_dwordx4 v235, v[56:59], s[10:11]
	v_add_u32_e32 v234, 0x16000, v235
	v_mul_f32_e32 v252, 0xbfb8aa3b, v240
	v_mul_f32_e32 v254, v240, v240
	v_rcp_f32_e32 v254, v254
	v_pk_mul_f32 v[40:41], v[44:45], v[40:41]
	v_pk_mul_f32 v[42:43], v[46:47], v[42:43]
	v_pk_mul_f32 v[32:33], v[36:37], v[32:33]
	v_pk_mul_f32 v[34:35], v[38:39], v[34:35]
	v_pk_mul_f32 v[44:45], v[44:45], v[252:253] op_sel_hi:[1,0]
	v_pk_mul_f32 v[46:47], v[46:47], v[252:253] op_sel_hi:[1,0]
	v_pk_mul_f32 v[36:37], v[36:37], v[252:253] op_sel_hi:[1,0]
	v_pk_mul_f32 v[38:39], v[38:39], v[252:253] op_sel_hi:[1,0]
	v_exp_f32_e32 v44, v44
	v_exp_f32_e32 v45, v45
	v_exp_f32_e32 v46, v46
	v_exp_f32_e32 v47, v47
	v_exp_f32_e32 v36, v36
	v_exp_f32_e32 v37, v37
	v_exp_f32_e32 v38, v38
	v_exp_f32_e32 v39, v39
	v_pk_fma_f32 v[44:45], v[44:45], v[254:255], v[254:255] op_sel_hi:[1,0,0]
	v_pk_fma_f32 v[46:47], v[46:47], v[254:255], v[254:255] op_sel_hi:[1,0,0]
	v_pk_fma_f32 v[36:37], v[36:37], v[254:255], v[254:255] op_sel_hi:[1,0,0]
	v_pk_fma_f32 v[38:39], v[38:39], v[254:255], v[254:255] op_sel_hi:[1,0,0]
	v_mul_f32_e32 v238, v44, v45
	v_mul_f32_e32 v242, v46, v47
	v_mul_f32_e32 v246, v36, v37
	v_mul_f32_e32 v250, v38, v39
	v_rcp_f32_e32 v238, v238
	v_rcp_f32_e32 v242, v242
	v_rcp_f32_e32 v246, v246
	v_rcp_f32_e32 v250, v250
	v_pk_mul_f32 v[44:45], v[44:45], v[238:239] op_sel:[1,0] op_sel_hi:[0,0]
	v_pk_mul_f32 v[46:47], v[46:47], v[242:243] op_sel:[1,0] op_sel_hi:[0,0]
	v_pk_mul_f32 v[36:37], v[36:37], v[246:247] op_sel:[1,0] op_sel_hi:[0,0]
	v_pk_mul_f32 v[38:39], v[38:39], v[250:251] op_sel:[1,0] op_sel_hi:[0,0]
	v_pk_mul_f32 v[40:41], v[40:41], v[44:45]
	v_pk_mul_f32 v[42:43], v[42:43], v[46:47]
	v_pk_mul_f32 v[32:33], v[32:33], v[36:37]
	v_pk_mul_f32 v[34:35], v[34:35], v[38:39]
	v_cvt_pk_bf16_f32 v40, v40, v41
	v_cvt_pk_bf16_f32 v41, v42, v43
	v_cvt_pk_bf16_f32 v42, v32, v33
	v_cvt_pk_bf16_f32 v43, v34, v35
	global_store_dwordx4 v234, v[40:43], s[10:11]
	v_add_u32_e32 v235, 0x16000, v234
	v_mul_f32_e32 v252, 0xbfb8aa3b, v244
	v_mul_f32_e32 v254, v244, v244
	v_rcp_f32_e32 v254, v254
	v_pk_mul_f32 v[24:25], v[28:29], v[24:25]
	v_pk_mul_f32 v[26:27], v[30:31], v[26:27]
	v_pk_mul_f32 v[16:17], v[20:21], v[16:17]
	v_pk_mul_f32 v[18:19], v[22:23], v[18:19]
	v_pk_mul_f32 v[28:29], v[28:29], v[252:253] op_sel_hi:[1,0]
	v_pk_mul_f32 v[30:31], v[30:31], v[252:253] op_sel_hi:[1,0]
	v_pk_mul_f32 v[20:21], v[20:21], v[252:253] op_sel_hi:[1,0]
	v_pk_mul_f32 v[22:23], v[22:23], v[252:253] op_sel_hi:[1,0]
	v_exp_f32_e32 v28, v28
	v_exp_f32_e32 v29, v29
	v_exp_f32_e32 v30, v30
	v_exp_f32_e32 v31, v31
	v_exp_f32_e32 v20, v20
	v_exp_f32_e32 v21, v21
	v_exp_f32_e32 v22, v22
	v_exp_f32_e32 v23, v23
	v_pk_fma_f32 v[28:29], v[28:29], v[254:255], v[254:255] op_sel_hi:[1,0,0]
	v_pk_fma_f32 v[30:31], v[30:31], v[254:255], v[254:255] op_sel_hi:[1,0,0]
	v_pk_fma_f32 v[20:21], v[20:21], v[254:255], v[254:255] op_sel_hi:[1,0,0]
	v_pk_fma_f32 v[22:23], v[22:23], v[254:255], v[254:255] op_sel_hi:[1,0,0]
	v_mul_f32_e32 v238, v28, v29
	v_mul_f32_e32 v242, v30, v31
	v_mul_f32_e32 v246, v20, v21
	v_mul_f32_e32 v250, v22, v23
	v_rcp_f32_e32 v238, v238
	v_rcp_f32_e32 v242, v242
	v_rcp_f32_e32 v246, v246
	v_rcp_f32_e32 v250, v250
	v_pk_mul_f32 v[28:29], v[28:29], v[238:239] op_sel:[1,0] op_sel_hi:[0,0]
	v_pk_mul_f32 v[30:31], v[30:31], v[242:243] op_sel:[1,0] op_sel_hi:[0,0]
	v_pk_mul_f32 v[20:21], v[20:21], v[246:247] op_sel:[1,0] op_sel_hi:[0,0]
	v_pk_mul_f32 v[22:23], v[22:23], v[250:251] op_sel:[1,0] op_sel_hi:[0,0]
	v_pk_mul_f32 v[24:25], v[24:25], v[28:29]
	v_pk_mul_f32 v[26:27], v[26:27], v[30:31]
	v_pk_mul_f32 v[16:17], v[16:17], v[20:21]
	v_pk_mul_f32 v[18:19], v[18:19], v[22:23]
	v_cvt_pk_bf16_f32 v24, v24, v25
	v_cvt_pk_bf16_f32 v25, v26, v27
	v_cvt_pk_bf16_f32 v26, v16, v17
	v_cvt_pk_bf16_f32 v27, v18, v19
	global_store_dwordx4 v235, v[24:27], s[10:11]
	v_add_u32_e32 v234, 0x16000, v235
	v_mul_f32_e32 v252, 0xbfb8aa3b, v248
	v_mul_f32_e32 v254, v248, v248
	v_rcp_f32_e32 v254, v254
	v_pk_mul_f32 v[8:9], v[12:13], v[8:9]
	v_pk_mul_f32 v[10:11], v[14:15], v[10:11]
	v_pk_mul_f32 v[0:1], v[4:5], v[0:1]
	v_pk_mul_f32 v[2:3], v[6:7], v[2:3]
	v_pk_mul_f32 v[12:13], v[12:13], v[252:253] op_sel_hi:[1,0]
	v_pk_mul_f32 v[14:15], v[14:15], v[252:253] op_sel_hi:[1,0]
	v_pk_mul_f32 v[4:5], v[4:5], v[252:253] op_sel_hi:[1,0]
	v_pk_mul_f32 v[6:7], v[6:7], v[252:253] op_sel_hi:[1,0]
	v_exp_f32_e32 v12, v12
	v_exp_f32_e32 v13, v13
	v_exp_f32_e32 v14, v14
	v_exp_f32_e32 v15, v15
	v_exp_f32_e32 v4, v4
	v_exp_f32_e32 v5, v5
	v_exp_f32_e32 v6, v6
	v_exp_f32_e32 v7, v7
	v_pk_fma_f32 v[12:13], v[12:13], v[254:255], v[254:255] op_sel_hi:[1,0,0]
	v_pk_fma_f32 v[14:15], v[14:15], v[254:255], v[254:255] op_sel_hi:[1,0,0]
	v_pk_fma_f32 v[4:5], v[4:5], v[254:255], v[254:255] op_sel_hi:[1,0,0]
	v_pk_fma_f32 v[6:7], v[6:7], v[254:255], v[254:255] op_sel_hi:[1,0,0]
	v_mul_f32_e32 v238, v12, v13
	v_mul_f32_e32 v242, v14, v15
	v_mul_f32_e32 v246, v4, v5
	v_mul_f32_e32 v250, v6, v7
	v_rcp_f32_e32 v238, v238
	v_rcp_f32_e32 v242, v242
	v_rcp_f32_e32 v246, v246
	v_rcp_f32_e32 v250, v250
	v_pk_mul_f32 v[12:13], v[12:13], v[238:239] op_sel:[1,0] op_sel_hi:[0,0]
	v_pk_mul_f32 v[14:15], v[14:15], v[242:243] op_sel:[1,0] op_sel_hi:[0,0]
	v_pk_mul_f32 v[4:5], v[4:5], v[246:247] op_sel:[1,0] op_sel_hi:[0,0]
	v_pk_mul_f32 v[6:7], v[6:7], v[250:251] op_sel:[1,0] op_sel_hi:[0,0]
	v_pk_mul_f32 v[8:9], v[8:9], v[12:13]
	v_pk_mul_f32 v[10:11], v[10:11], v[14:15]
	v_pk_mul_f32 v[0:1], v[0:1], v[4:5]
	v_pk_mul_f32 v[2:3], v[2:3], v[6:7]
	v_cvt_pk_bf16_f32 v8, v8, v9
	v_cvt_pk_bf16_f32 v9, v10, v11
	v_cvt_pk_bf16_f32 v10, v0, v1
	v_cvt_pk_bf16_f32 v11, v2, v3
	global_store_dwordx4 v234, v[8:11], s[10:11]
	s_andn2_b64 vcc, exec, s[4:5]
	s_mov_b64 s[4:5], -1
	s_cbranch_vccnz .LBB0_71
	s_andn2_b64 vcc, exec, s[8:9]
	s_cbranch_vccnz .LBB0_70
	s_barrier
	s_branch .LBB0_70

.Llast_4:
	v_add_u32_e32 v153, s66, v147
	ds_read_b128 v[160:163], v153
	v_xor_b32_e32 v253, 64, v153
	ds_read_b128 v[164:167], v253
	ds_read_b128 v[168:171], v153 offset:2048
	ds_read_b128 v[172:175], v253 offset:2048
	v_add_u32_e32 v153, s67, v147
	ds_read_b128 v[176:179], v153
	v_xor_b32_e32 v253, 64, v153
	ds_read_b128 v[180:183], v253
	ds_read_b128 v[186:189], v153 offset:2048
	ds_read_b128 v[190:193], v253 offset:2048
	s_add_u32 s50, s46, 0xfffc0080
	s_addc_u32 s51, s47, -1
	s_and_b64 s[48:49], s[48:49], exec
	s_cselect_b32 s51, s29, s51
	s_cselect_b32 s50, s70, s50
	s_cselect_b32 s49, s71, s74
	s_cselect_b32 s48, s72, s73
	v_lshl_add_u64 v[154:155], s[46:47], 0, v[138:139]
	s_add_i32 m0, s57, 0xc000
	ds_read_b128 v[194:197], v150
	v_xor_b32_e32 v253, 64, v150
	ds_read_b128 v[198:201], v253
	ds_read_b128 v[202:205], v150 offset:2048
	ds_read_b128 v[206:209], v253 offset:2048
	ds_read_b128 v[210:213], v150 offset:4096
	ds_read_b128 v[214:217], v253 offset:4096
	ds_read_b128 v[218:221], v150 offset:6144
	ds_read_b128 v[222:225], v253 offset:6144
	global_load_lds_dwordx4 v[154:155], off
	v_lshl_add_u64 v[154:155], s[46:47], 0, v[136:137]
	s_add_i32 m0, s57, 0xe000
	s_nop 0
	global_load_lds_dwordx4 v[154:155], off
	s_waitcnt vmcnt(8)
	s_waitcnt lgkmcnt(0)
	s_setprio 1
	s_barrier
	v_mfma_f32_16x16x32_bf16 v[124:127], v[160:163], v[194:197], v[124:127]
	v_mfma_f32_16x16x32_bf16 v[124:127], v[164:167], v[198:201], v[124:127]
	v_mfma_f32_16x16x32_bf16 v[116:119], v[172:175], v[198:201], v[116:119]
	v_mfma_f32_16x16x32_bf16 v[116:119], v[168:171], v[194:197], v[116:119]
	v_mfma_f32_16x16x32_bf16 v[100:103], v[168:171], v[202:205], v[100:103]
	v_mfma_f32_16x16x32_bf16 v[100:103], v[172:175], v[206:209], v[100:103]
	v_mfma_f32_16x16x32_bf16 v[108:111], v[164:167], v[206:209], v[108:111]
	v_mfma_f32_16x16x32_bf16 v[108:111], v[160:163], v[202:205], v[108:111]
	v_mfma_f32_16x16x32_bf16 v[92:95], v[160:163], v[210:213], v[92:95]
	v_mfma_f32_16x16x32_bf16 v[92:95], v[164:167], v[214:217], v[92:95]
	v_mfma_f32_16x16x32_bf16 v[84:87], v[172:175], v[214:217], v[84:87]
	v_mfma_f32_16x16x32_bf16 v[84:87], v[168:171], v[210:213], v[84:87]
	v_mfma_f32_16x16x32_bf16 v[68:71], v[168:171], v[218:221], v[68:71]
	v_mfma_f32_16x16x32_bf16 v[68:71], v[172:175], v[222:225], v[68:71]
	v_mfma_f32_16x16x32_bf16 v[76:79], v[164:167], v[222:225], v[76:79]
	v_mfma_f32_16x16x32_bf16 v[76:79], v[160:163], v[218:221], v[76:79]
	s_setprio 0
	s_setprio 1
	v_mfma_f32_16x16x32_bf16 v[120:123], v[176:179], v[194:197], v[120:123]
	v_mfma_f32_16x16x32_bf16 v[120:123], v[180:183], v[198:201], v[120:123]
	v_mfma_f32_16x16x32_bf16 v[112:115], v[190:193], v[198:201], v[112:115]
	v_mfma_f32_16x16x32_bf16 v[112:115], v[186:189], v[194:197], v[112:115]
	v_mfma_f32_16x16x32_bf16 v[96:99], v[186:189], v[202:205], v[96:99]
	v_mfma_f32_16x16x32_bf16 v[96:99], v[190:193], v[206:209], v[96:99]
	v_mfma_f32_16x16x32_bf16 v[104:107], v[180:183], v[206:209], v[104:107]
	v_mfma_f32_16x16x32_bf16 v[104:107], v[176:179], v[202:205], v[104:107]
	v_mfma_f32_16x16x32_bf16 v[88:91], v[176:179], v[210:213], v[88:91]
	v_mfma_f32_16x16x32_bf16 v[88:91], v[180:183], v[214:217], v[88:91]
	v_mfma_f32_16x16x32_bf16 v[80:83], v[190:193], v[214:217], v[80:83]
	v_mfma_f32_16x16x32_bf16 v[80:83], v[186:189], v[210:213], v[80:83]
	v_mfma_f32_16x16x32_bf16 v[64:67], v[186:189], v[218:221], v[64:67]
	v_mfma_f32_16x16x32_bf16 v[64:67], v[190:193], v[222:225], v[64:67]
	v_mfma_f32_16x16x32_bf16 v[72:75], v[180:183], v[222:225], v[72:75]
	v_mfma_f32_16x16x32_bf16 v[72:75], v[176:179], v[218:221], v[72:75]
	s_barrier
	s_setprio 0
	s_add_i32 s76, s66, s54
	v_lshl_add_u64 v[154:155], s[48:49], 0, v[132:133]
	s_mov_b32 m0, s76
	ds_read_b128 v[194:197], v150 offset:16384
	v_xor_b32_e32 v253, 64, v150
	ds_read_b128 v[198:201], v253 offset:16384
	ds_read_b128 v[202:205], v150 offset:18432
	ds_read_b128 v[206:209], v253 offset:18432
	ds_read_b128 v[210:213], v150 offset:20480
	ds_read_b128 v[214:217], v253 offset:20480
	ds_read_b128 v[218:221], v150 offset:22528
	ds_read_b128 v[222:225], v253 offset:22528
	global_load_lds_dwordx4 v[154:155], off
	s_add_i32 m0, s76, 0x2000
	s_add_u32 s76, s48, 0x40000
	v_lshl_add_u64 v[226:227], s[48:49], 0, v[128:129]
	s_addc_u32 s77, s49, 0
	s_add_i32 s78, s67, s54
	global_load_lds_dwordx4 v[226:227], off
	v_lshl_add_u64 v[228:229], s[76:77], 0, v[132:133]
	s_mov_b32 m0, s78
	v_lshl_add_u64 v[230:231], s[50:51], 0, v[130:131]
	global_load_lds_dwordx4 v[228:229], off
	v_lshl_add_u64 v[228:229], s[76:77], 0, v[128:129]
	s_add_i32 m0, s78, 0x2000
	s_nop 0
	global_load_lds_dwordx4 v[228:229], off
	v_lshl_add_u64 v[228:229], s[50:51], 0, v[134:135]
	s_mov_b32 m0, s57
	s_nop 0
	global_load_lds_dwordx4 v[228:229], off
	s_mov_b32 m0, s58
	s_nop 0
	global_load_lds_dwordx4 v[230:231], off
	s_waitcnt vmcnt(8)
	s_waitcnt lgkmcnt(0)
	s_setprio 1
	s_barrier
	v_mfma_f32_16x16x32_bf16 v[60:63], v[160:163], v[194:197], v[60:63]
	v_mfma_f32_16x16x32_bf16 v[60:63], v[164:167], v[198:201], v[60:63]
	v_mfma_f32_16x16x32_bf16 v[52:55], v[172:175], v[198:201], v[52:55]
	v_mfma_f32_16x16x32_bf16 v[52:55], v[168:171], v[194:197], v[52:55]
	v_mfma_f32_16x16x32_bf16 v[36:39], v[168:171], v[202:205], v[36:39]
	v_mfma_f32_16x16x32_bf16 v[36:39], v[172:175], v[206:209], v[36:39]
	v_mfma_f32_16x16x32_bf16 v[44:47], v[164:167], v[206:209], v[44:47]
	v_mfma_f32_16x16x32_bf16 v[44:47], v[160:163], v[202:205], v[44:47]
	v_mfma_f32_16x16x32_bf16 v[28:31], v[160:163], v[210:213], v[28:31]
	v_mfma_f32_16x16x32_bf16 v[28:31], v[164:167], v[214:217], v[28:31]
	v_mfma_f32_16x16x32_bf16 v[20:23], v[172:175], v[214:217], v[20:23]
	v_mfma_f32_16x16x32_bf16 v[20:23], v[168:171], v[210:213], v[20:23]
	v_mfma_f32_16x16x32_bf16 v[4:7], v[168:171], v[218:221], v[4:7]
	v_mfma_f32_16x16x32_bf16 v[4:7], v[172:175], v[222:225], v[4:7]
	v_mfma_f32_16x16x32_bf16 v[12:15], v[164:167], v[222:225], v[12:15]
	v_mfma_f32_16x16x32_bf16 v[12:15], v[160:163], v[218:221], v[12:15]
	s_setprio 0
	s_setprio 1
	v_mfma_f32_16x16x32_bf16 v[56:59], v[176:179], v[194:197], v[56:59]
	v_mfma_f32_16x16x32_bf16 v[56:59], v[180:183], v[198:201], v[56:59]
	v_mfma_f32_16x16x32_bf16 v[48:51], v[190:193], v[198:201], v[48:51]
	v_mfma_f32_16x16x32_bf16 v[48:51], v[186:189], v[194:197], v[48:51]
	v_mfma_f32_16x16x32_bf16 v[32:35], v[186:189], v[202:205], v[32:35]
	v_mfma_f32_16x16x32_bf16 v[32:35], v[190:193], v[206:209], v[32:35]
	v_mfma_f32_16x16x32_bf16 v[40:43], v[180:183], v[206:209], v[40:43]
	v_mfma_f32_16x16x32_bf16 v[40:43], v[176:179], v[202:205], v[40:43]
	v_mfma_f32_16x16x32_bf16 v[24:27], v[176:179], v[210:213], v[24:27]
	v_mfma_f32_16x16x32_bf16 v[24:27], v[180:183], v[214:217], v[24:27]
	v_mfma_f32_16x16x32_bf16 v[16:19], v[190:193], v[214:217], v[16:19]
	v_mfma_f32_16x16x32_bf16 v[16:19], v[186:189], v[210:213], v[16:19]
	v_mfma_f32_16x16x32_bf16 v[0:3], v[186:189], v[218:221], v[0:3]
	v_mfma_f32_16x16x32_bf16 v[0:3], v[190:193], v[222:225], v[0:3]
	v_mfma_f32_16x16x32_bf16 v[8:11], v[180:183], v[222:225], v[8:11]
	v_mfma_f32_16x16x32_bf16 v[8:11], v[176:179], v[218:221], v[8:11]
	s_barrier
	s_setprio 0
	s_add_i32 s76, 0, 0x18000
	v_add_u32_e32 v153, s76, v147
	s_add_i32 s77, 0, 0x1c000
	ds_read_b128 v[160:163], v153
	v_xor_b32_e32 v253, 64, v153
	ds_read_b128 v[164:167], v253
	ds_read_b128 v[168:171], v153 offset:2048
	ds_read_b128 v[172:175], v253 offset:2048
	v_add_u32_e32 v153, s77, v147
	ds_read_b128 v[176:179], v153
	v_xor_b32_e32 v253, 64, v153
	ds_read_b128 v[180:183], v253
	ds_read_b128 v[186:189], v153 offset:2048
	ds_read_b128 v[190:193], v253 offset:2048
	s_add_u32 s50, s50, 0x40000
	s_addc_u32 s51, s51, 0
	s_mov_b32 m0, s59
	v_lshl_add_u64 v[232:233], s[50:51], 0, v[134:135]
	ds_read_b128 v[194:197], v150 offset:32768
	v_xor_b32_e32 v253, 64, v150
	ds_read_b128 v[198:201], v253 offset:32768
	ds_read_b128 v[202:205], v150 offset:34816
	ds_read_b128 v[206:209], v253 offset:34816
	ds_read_b128 v[210:213], v150 offset:36864
	ds_read_b128 v[214:217], v253 offset:36864
	ds_read_b128 v[218:221], v150 offset:38912
	ds_read_b128 v[222:225], v253 offset:38912
	global_load_lds_dwordx4 v[232:233], off
	v_lshl_add_u64 v[232:233], s[50:51], 0, v[130:131]
	s_mov_b32 m0, s60
	s_nop 0
	global_load_lds_dwordx4 v[232:233], off
	s_waitcnt vmcnt(8)
	s_waitcnt lgkmcnt(0)
	s_setprio 1
	s_barrier
	v_mfma_f32_16x16x32_bf16 v[124:127], v[160:163], v[194:197], v[124:127]
	v_mfma_f32_16x16x32_bf16 v[124:127], v[164:167], v[198:201], v[124:127]
	v_mfma_f32_16x16x32_bf16 v[116:119], v[172:175], v[198:201], v[116:119]
	v_mfma_f32_16x16x32_bf16 v[116:119], v[168:171], v[194:197], v[116:119]
	v_mfma_f32_16x16x32_bf16 v[100:103], v[168:171], v[202:205], v[100:103]
	v_mfma_f32_16x16x32_bf16 v[100:103], v[172:175], v[206:209], v[100:103]
	v_mfma_f32_16x16x32_bf16 v[108:111], v[164:167], v[206:209], v[108:111]
	v_mfma_f32_16x16x32_bf16 v[108:111], v[160:163], v[202:205], v[108:111]
	v_mfma_f32_16x16x32_bf16 v[92:95], v[160:163], v[210:213], v[92:95]
	v_mfma_f32_16x16x32_bf16 v[92:95], v[164:167], v[214:217], v[92:95]
	v_mfma_f32_16x16x32_bf16 v[84:87], v[172:175], v[214:217], v[84:87]
	v_mfma_f32_16x16x32_bf16 v[84:87], v[168:171], v[210:213], v[84:87]
	v_mfma_f32_16x16x32_bf16 v[68:71], v[168:171], v[218:221], v[68:71]
	v_mfma_f32_16x16x32_bf16 v[68:71], v[172:175], v[222:225], v[68:71]
	v_mfma_f32_16x16x32_bf16 v[76:79], v[164:167], v[222:225], v[76:79]
	v_mfma_f32_16x16x32_bf16 v[76:79], v[160:163], v[218:221], v[76:79]
	s_setprio 0
	s_setprio 1
	v_mfma_f32_16x16x32_bf16 v[120:123], v[176:179], v[194:197], v[120:123]
	v_mfma_f32_16x16x32_bf16 v[120:123], v[180:183], v[198:201], v[120:123]
	v_mfma_f32_16x16x32_bf16 v[112:115], v[190:193], v[198:201], v[112:115]
	v_mfma_f32_16x16x32_bf16 v[112:115], v[186:189], v[194:197], v[112:115]
	v_mfma_f32_16x16x32_bf16 v[96:99], v[186:189], v[202:205], v[96:99]
	v_mfma_f32_16x16x32_bf16 v[96:99], v[190:193], v[206:209], v[96:99]
	v_mfma_f32_16x16x32_bf16 v[104:107], v[180:183], v[206:209], v[104:107]
	v_mfma_f32_16x16x32_bf16 v[104:107], v[176:179], v[202:205], v[104:107]
	v_mfma_f32_16x16x32_bf16 v[88:91], v[176:179], v[210:213], v[88:91]
	v_mfma_f32_16x16x32_bf16 v[88:91], v[180:183], v[214:217], v[88:91]
	v_mfma_f32_16x16x32_bf16 v[80:83], v[190:193], v[214:217], v[80:83]
	v_mfma_f32_16x16x32_bf16 v[80:83], v[186:189], v[210:213], v[80:83]
	v_mfma_f32_16x16x32_bf16 v[64:67], v[186:189], v[218:221], v[64:67]
	v_mfma_f32_16x16x32_bf16 v[64:67], v[190:193], v[222:225], v[64:67]
	v_mfma_f32_16x16x32_bf16 v[72:75], v[180:183], v[222:225], v[72:75]
	v_mfma_f32_16x16x32_bf16 v[72:75], v[176:179], v[218:221], v[72:75]
	s_barrier
	s_setprio 0
	v_add_u32_e32 v234, 0x21000, v151
	ds_read_b128 v[236:239], v234
	ds_read_b128 v[240:243], v234 offset:256
	ds_read_b128 v[244:247], v234 offset:512
	ds_read_b128 v[248:251], v234 offset:768
	v_add_u32_e32 v235, s27, v146
	v_mul_u32_u24_e32 v235, 0x1600, v235
	v_lshl_or_b32 v234, s69, 7, v149
	v_lshl_add_u32 v235, v234, 1, v235
	s_add_i32 s50, s76, s54
	v_lshl_add_u64 v[154:155], v[154:155], 0, s[20:21]
	s_mov_b32 m0, s50
	ds_read_b128 v[194:197], v150 offset:49152
	v_xor_b32_e32 v253, 64, v150
	ds_read_b128 v[198:201], v253 offset:49152
	ds_read_b128 v[202:205], v150 offset:51200
	ds_read_b128 v[206:209], v253 offset:51200
	ds_read_b128 v[210:213], v150 offset:53248
	ds_read_b128 v[214:217], v253 offset:53248
	ds_read_b128 v[218:221], v150 offset:55296
	ds_read_b128 v[222:225], v253 offset:55296
	global_load_lds_dwordx4 v[154:155], off
	s_add_i32 m0, s50, 0x2000
	s_add_u32 s48, s48, 0x40080
	v_lshl_add_u64 v[154:155], v[226:227], 0, s[20:21]
	s_addc_u32 s49, s49, 0
	s_add_i32 s50, s77, s54
	global_load_lds_dwordx4 v[154:155], off
	v_lshl_add_u64 v[154:155], s[48:49], 0, v[132:133]
	s_mov_b32 m0, s50
	s_nop 0
	global_load_lds_dwordx4 v[154:155], off
	v_lshl_add_u64 v[154:155], s[48:49], 0, v[128:129]
	s_add_i32 m0, s50, 0x2000
	s_nop 0
	global_load_lds_dwordx4 v[154:155], off
	v_lshl_add_u64 v[154:155], v[228:229], 0, s[20:21]
	s_mov_b32 m0, s62
	s_nop 0
	global_load_lds_dwordx4 v[154:155], off
	v_lshl_add_u64 v[154:155], v[230:231], 0, s[20:21]
	s_mov_b32 m0, s63
	s_nop 0
	global_load_lds_dwordx4 v[154:155], off
	s_waitcnt lgkmcnt(8)
	v_add_f32_e32 v236, v236, v237
	v_add_f32_e32 v238, v238, v239
	v_add_f32_e32 v240, v240, v241
	v_add_f32_e32 v242, v242, v243
	v_add_f32_e32 v244, v244, v245
	v_add_f32_e32 v246, v246, v247
	v_add_f32_e32 v248, v248, v249
	v_add_f32_e32 v250, v250, v251
	v_add_f32_e32 v236, v236, v238
	v_add_f32_e32 v240, v240, v242
	v_add_f32_e32 v244, v244, v246
	v_add_f32_e32 v248, v248, v250
	v_fmamk_f32 v236, v236, 0x3a800000, v152
	v_fmamk_f32 v240, v240, 0x3a800000, v152
	v_fmamk_f32 v244, v244, 0x3a800000, v152
	v_fmamk_f32 v248, v248, 0x3a800000, v152
	v_rsq_f32_e32 v236, v236
	v_rsq_f32_e32 v240, v240
	v_rsq_f32_e32 v244, v244
	v_rsq_f32_e32 v248, v248
	v_mul_f32_e32 v252, 0xbfb8aa3b, v236
	v_mul_f32_e32 v254, v236, v236
	v_rcp_f32_e32 v254, v254
	v_pk_mul_f32 v[120:121], v[124:125], v[120:121]
	v_pk_mul_f32 v[122:123], v[126:127], v[122:123]
	v_pk_mul_f32 v[112:113], v[116:117], v[112:113]
	v_pk_mul_f32 v[114:115], v[118:119], v[114:115]
	v_pk_mul_f32 v[124:125], v[124:125], v[252:253] op_sel_hi:[1,0]
	v_pk_mul_f32 v[126:127], v[126:127], v[252:253] op_sel_hi:[1,0]
	v_pk_mul_f32 v[116:117], v[116:117], v[252:253] op_sel_hi:[1,0]
	v_pk_mul_f32 v[118:119], v[118:119], v[252:253] op_sel_hi:[1,0]
	v_exp_f32_e32 v124, v124
	v_exp_f32_e32 v125, v125
	v_exp_f32_e32 v126, v126
	v_exp_f32_e32 v127, v127
	v_exp_f32_e32 v116, v116
	v_exp_f32_e32 v117, v117
	v_exp_f32_e32 v118, v118
	v_exp_f32_e32 v119, v119
	v_pk_fma_f32 v[124:125], v[124:125], v[254:255], v[254:255] op_sel_hi:[1,0,0]
	v_pk_fma_f32 v[126:127], v[126:127], v[254:255], v[254:255] op_sel_hi:[1,0,0]
	v_pk_fma_f32 v[116:117], v[116:117], v[254:255], v[254:255] op_sel_hi:[1,0,0]
	v_pk_fma_f32 v[118:119], v[118:119], v[254:255], v[254:255] op_sel_hi:[1,0,0]
	v_mul_f32_e32 v238, v124, v125
	v_mul_f32_e32 v242, v126, v127
	v_mul_f32_e32 v246, v116, v117
	v_mul_f32_e32 v250, v118, v119
	v_rcp_f32_e32 v238, v238
	v_rcp_f32_e32 v242, v242
	v_rcp_f32_e32 v246, v246
	v_rcp_f32_e32 v250, v250
	v_pk_mul_f32 v[124:125], v[124:125], v[238:239] op_sel:[1,0] op_sel_hi:[0,0]
	v_pk_mul_f32 v[126:127], v[126:127], v[242:243] op_sel:[1,0] op_sel_hi:[0,0]
	v_pk_mul_f32 v[116:117], v[116:117], v[246:247] op_sel:[1,0] op_sel_hi:[0,0]
	v_pk_mul_f32 v[118:119], v[118:119], v[250:251] op_sel:[1,0] op_sel_hi:[0,0]
	v_pk_mul_f32 v[120:121], v[120:121], v[124:125]
	v_pk_mul_f32 v[122:123], v[122:123], v[126:127]
	v_pk_mul_f32 v[112:113], v[112:113], v[116:117]
	v_pk_mul_f32 v[114:115], v[114:115], v[118:119]
	v_cvt_pk_bf16_f32 v120, v120, v121
	v_cvt_pk_bf16_f32 v121, v122, v123
	v_cvt_pk_bf16_f32 v122, v112, v113
	v_cvt_pk_bf16_f32 v123, v114, v115
	global_store_dwordx4 v235, v[120:123], s[14:15]
	v_add_u32_e32 v234, 0x16000, v235
	v_mul_f32_e32 v252, 0xbfb8aa3b, v240
	v_mul_f32_e32 v254, v240, v240
	v_rcp_f32_e32 v254, v254
	v_pk_mul_f32 v[104:105], v[108:109], v[104:105]
	v_pk_mul_f32 v[106:107], v[110:111], v[106:107]
	v_pk_mul_f32 v[96:97], v[100:101], v[96:97]
	v_pk_mul_f32 v[98:99], v[102:103], v[98:99]
	v_pk_mul_f32 v[108:109], v[108:109], v[252:253] op_sel_hi:[1,0]
	v_pk_mul_f32 v[110:111], v[110:111], v[252:253] op_sel_hi:[1,0]
	v_pk_mul_f32 v[100:101], v[100:101], v[252:253] op_sel_hi:[1,0]
	v_pk_mul_f32 v[102:103], v[102:103], v[252:253] op_sel_hi:[1,0]
	v_exp_f32_e32 v108, v108
	v_exp_f32_e32 v109, v109
	v_exp_f32_e32 v110, v110
	v_exp_f32_e32 v111, v111
	v_exp_f32_e32 v100, v100
	v_exp_f32_e32 v101, v101
	v_exp_f32_e32 v102, v102
	v_exp_f32_e32 v103, v103
	v_pk_fma_f32 v[108:109], v[108:109], v[254:255], v[254:255] op_sel_hi:[1,0,0]
	v_pk_fma_f32 v[110:111], v[110:111], v[254:255], v[254:255] op_sel_hi:[1,0,0]
	v_pk_fma_f32 v[100:101], v[100:101], v[254:255], v[254:255] op_sel_hi:[1,0,0]
	v_pk_fma_f32 v[102:103], v[102:103], v[254:255], v[254:255] op_sel_hi:[1,0,0]
	v_mul_f32_e32 v238, v108, v109
	v_mul_f32_e32 v242, v110, v111
	v_mul_f32_e32 v246, v100, v101
	v_mul_f32_e32 v250, v102, v103
	v_rcp_f32_e32 v238, v238
	v_rcp_f32_e32 v242, v242
	v_rcp_f32_e32 v246, v246
	v_rcp_f32_e32 v250, v250
	v_pk_mul_f32 v[108:109], v[108:109], v[238:239] op_sel:[1,0] op_sel_hi:[0,0]
	v_pk_mul_f32 v[110:111], v[110:111], v[242:243] op_sel:[1,0] op_sel_hi:[0,0]
	v_pk_mul_f32 v[100:101], v[100:101], v[246:247] op_sel:[1,0] op_sel_hi:[0,0]
	v_pk_mul_f32 v[102:103], v[102:103], v[250:251] op_sel:[1,0] op_sel_hi:[0,0]
	v_pk_mul_f32 v[104:105], v[104:105], v[108:109]
	v_pk_mul_f32 v[106:107], v[106:107], v[110:111]
	v_pk_mul_f32 v[96:97], v[96:97], v[100:101]
	v_pk_mul_f32 v[98:99], v[98:99], v[102:103]
	v_cvt_pk_bf16_f32 v104, v104, v105
	v_cvt_pk_bf16_f32 v105, v106, v107
	v_cvt_pk_bf16_f32 v106, v96, v97
	v_cvt_pk_bf16_f32 v107, v98, v99
	global_store_dwordx4 v234, v[104:107], s[14:15]
	v_add_u32_e32 v235, 0x16000, v234
	v_mul_f32_e32 v252, 0xbfb8aa3b, v244
	v_mul_f32_e32 v254, v244, v244
	v_rcp_f32_e32 v254, v254
	v_pk_mul_f32 v[88:89], v[92:93], v[88:89]
	v_pk_mul_f32 v[90:91], v[94:95], v[90:91]
	v_pk_mul_f32 v[80:81], v[84:85], v[80:81]
	v_pk_mul_f32 v[82:83], v[86:87], v[82:83]
	v_pk_mul_f32 v[92:93], v[92:93], v[252:253] op_sel_hi:[1,0]
	v_pk_mul_f32 v[94:95], v[94:95], v[252:253] op_sel_hi:[1,0]
	v_pk_mul_f32 v[84:85], v[84:85], v[252:253] op_sel_hi:[1,0]
	v_pk_mul_f32 v[86:87], v[86:87], v[252:253] op_sel_hi:[1,0]
	v_exp_f32_e32 v92, v92
	v_exp_f32_e32 v93, v93
	v_exp_f32_e32 v94, v94
	v_exp_f32_e32 v95, v95
	v_exp_f32_e32 v84, v84
	v_exp_f32_e32 v85, v85
	v_exp_f32_e32 v86, v86
	v_exp_f32_e32 v87, v87
	v_pk_fma_f32 v[92:93], v[92:93], v[254:255], v[254:255] op_sel_hi:[1,0,0]
	v_pk_fma_f32 v[94:95], v[94:95], v[254:255], v[254:255] op_sel_hi:[1,0,0]
	v_pk_fma_f32 v[84:85], v[84:85], v[254:255], v[254:255] op_sel_hi:[1,0,0]
	v_pk_fma_f32 v[86:87], v[86:87], v[254:255], v[254:255] op_sel_hi:[1,0,0]
	v_mul_f32_e32 v238, v92, v93
	v_mul_f32_e32 v242, v94, v95
	v_mul_f32_e32 v246, v84, v85
	v_mul_f32_e32 v250, v86, v87
	v_rcp_f32_e32 v238, v238
	v_rcp_f32_e32 v242, v242
	v_rcp_f32_e32 v246, v246
	v_rcp_f32_e32 v250, v250
	v_pk_mul_f32 v[92:93], v[92:93], v[238:239] op_sel:[1,0] op_sel_hi:[0,0]
	v_pk_mul_f32 v[94:95], v[94:95], v[242:243] op_sel:[1,0] op_sel_hi:[0,0]
	v_pk_mul_f32 v[84:85], v[84:85], v[246:247] op_sel:[1,0] op_sel_hi:[0,0]
	v_pk_mul_f32 v[86:87], v[86:87], v[250:251] op_sel:[1,0] op_sel_hi:[0,0]
	v_pk_mul_f32 v[88:89], v[88:89], v[92:93]
	v_pk_mul_f32 v[90:91], v[90:91], v[94:95]
	v_pk_mul_f32 v[80:81], v[80:81], v[84:85]
	v_pk_mul_f32 v[82:83], v[82:83], v[86:87]
	v_cvt_pk_bf16_f32 v88, v88, v89
	v_cvt_pk_bf16_f32 v89, v90, v91
	v_cvt_pk_bf16_f32 v90, v80, v81
	v_cvt_pk_bf16_f32 v91, v82, v83
	global_store_dwordx4 v235, v[88:91], s[14:15]
	v_add_u32_e32 v234, 0x16000, v235
	v_mul_f32_e32 v252, 0xbfb8aa3b, v248
	v_mul_f32_e32 v254, v248, v248
	v_rcp_f32_e32 v254, v254
	v_pk_mul_f32 v[72:73], v[76:77], v[72:73]
	v_pk_mul_f32 v[74:75], v[78:79], v[74:75]
	v_pk_mul_f32 v[64:65], v[68:69], v[64:65]
	v_pk_mul_f32 v[66:67], v[70:71], v[66:67]
	v_pk_mul_f32 v[76:77], v[76:77], v[252:253] op_sel_hi:[1,0]
	v_pk_mul_f32 v[78:79], v[78:79], v[252:253] op_sel_hi:[1,0]
	v_pk_mul_f32 v[68:69], v[68:69], v[252:253] op_sel_hi:[1,0]
	v_pk_mul_f32 v[70:71], v[70:71], v[252:253] op_sel_hi:[1,0]
	v_exp_f32_e32 v76, v76
	v_exp_f32_e32 v77, v77
	v_exp_f32_e32 v78, v78
	v_exp_f32_e32 v79, v79
	v_exp_f32_e32 v68, v68
	v_exp_f32_e32 v69, v69
	v_exp_f32_e32 v70, v70
	v_exp_f32_e32 v71, v71
	v_pk_fma_f32 v[76:77], v[76:77], v[254:255], v[254:255] op_sel_hi:[1,0,0]
	v_pk_fma_f32 v[78:79], v[78:79], v[254:255], v[254:255] op_sel_hi:[1,0,0]
	v_pk_fma_f32 v[68:69], v[68:69], v[254:255], v[254:255] op_sel_hi:[1,0,0]
	v_pk_fma_f32 v[70:71], v[70:71], v[254:255], v[254:255] op_sel_hi:[1,0,0]
	v_mul_f32_e32 v238, v76, v77
	v_mul_f32_e32 v242, v78, v79
	v_mul_f32_e32 v246, v68, v69
	v_mul_f32_e32 v250, v70, v71
	v_rcp_f32_e32 v238, v238
	v_rcp_f32_e32 v242, v242
	v_rcp_f32_e32 v246, v246
	v_rcp_f32_e32 v250, v250
	v_pk_mul_f32 v[76:77], v[76:77], v[238:239] op_sel:[1,0] op_sel_hi:[0,0]
	v_pk_mul_f32 v[78:79], v[78:79], v[242:243] op_sel:[1,0] op_sel_hi:[0,0]
	v_pk_mul_f32 v[68:69], v[68:69], v[246:247] op_sel:[1,0] op_sel_hi:[0,0]
	v_pk_mul_f32 v[70:71], v[70:71], v[250:251] op_sel:[1,0] op_sel_hi:[0,0]
	v_pk_mul_f32 v[72:73], v[72:73], v[76:77]
	v_pk_mul_f32 v[74:75], v[74:75], v[78:79]
	v_pk_mul_f32 v[64:65], v[64:65], v[68:69]
	v_pk_mul_f32 v[66:67], v[66:67], v[70:71]
	v_cvt_pk_bf16_f32 v72, v72, v73
	v_cvt_pk_bf16_f32 v73, v74, v75
	v_cvt_pk_bf16_f32 v74, v64, v65
	v_cvt_pk_bf16_f32 v75, v66, v67
	global_store_dwordx4 v234, v[72:75], s[14:15]
	s_waitcnt vmcnt(12)
	s_waitcnt lgkmcnt(0)
	s_setprio 1
	s_barrier
	v_mfma_f32_16x16x32_bf16 v[60:63], v[160:163], v[194:197], v[60:63]
	v_mfma_f32_16x16x32_bf16 v[60:63], v[164:167], v[198:201], v[60:63]
	v_mfma_f32_16x16x32_bf16 v[52:55], v[172:175], v[198:201], v[52:55]
	v_mfma_f32_16x16x32_bf16 v[52:55], v[168:171], v[194:197], v[52:55]
	v_mfma_f32_16x16x32_bf16 v[36:39], v[168:171], v[202:205], v[36:39]
	v_mfma_f32_16x16x32_bf16 v[36:39], v[172:175], v[206:209], v[36:39]
	v_mfma_f32_16x16x32_bf16 v[44:47], v[164:167], v[206:209], v[44:47]
	v_mfma_f32_16x16x32_bf16 v[44:47], v[160:163], v[202:205], v[44:47]
	v_mfma_f32_16x16x32_bf16 v[28:31], v[160:163], v[210:213], v[28:31]
	v_mfma_f32_16x16x32_bf16 v[28:31], v[164:167], v[214:217], v[28:31]
	v_mfma_f32_16x16x32_bf16 v[20:23], v[172:175], v[214:217], v[20:23]
	v_mfma_f32_16x16x32_bf16 v[20:23], v[168:171], v[210:213], v[20:23]
	v_mfma_f32_16x16x32_bf16 v[4:7], v[168:171], v[218:221], v[4:7]
	v_mfma_f32_16x16x32_bf16 v[4:7], v[172:175], v[222:225], v[4:7]
	v_mfma_f32_16x16x32_bf16 v[12:15], v[164:167], v[222:225], v[12:15]
	v_mfma_f32_16x16x32_bf16 v[12:15], v[160:163], v[218:221], v[12:15]
	s_setprio 0
	s_setprio 1
	v_mfma_f32_16x16x32_bf16 v[56:59], v[176:179], v[194:197], v[56:59]
	v_mfma_f32_16x16x32_bf16 v[56:59], v[180:183], v[198:201], v[56:59]
	v_mfma_f32_16x16x32_bf16 v[48:51], v[190:193], v[198:201], v[48:51]
	v_mfma_f32_16x16x32_bf16 v[48:51], v[186:189], v[194:197], v[48:51]
	v_mfma_f32_16x16x32_bf16 v[32:35], v[186:189], v[202:205], v[32:35]
	v_mfma_f32_16x16x32_bf16 v[32:35], v[190:193], v[206:209], v[32:35]
	v_mfma_f32_16x16x32_bf16 v[40:43], v[180:183], v[206:209], v[40:43]
	v_mfma_f32_16x16x32_bf16 v[40:43], v[176:179], v[202:205], v[40:43]
	v_mfma_f32_16x16x32_bf16 v[24:27], v[176:179], v[210:213], v[24:27]
	v_mfma_f32_16x16x32_bf16 v[24:27], v[180:183], v[214:217], v[24:27]
	v_mfma_f32_16x16x32_bf16 v[16:19], v[190:193], v[214:217], v[16:19]
	v_mfma_f32_16x16x32_bf16 v[16:19], v[186:189], v[210:213], v[16:19]
	v_mfma_f32_16x16x32_bf16 v[0:3], v[186:189], v[218:221], v[0:3]
	v_mfma_f32_16x16x32_bf16 v[0:3], v[190:193], v[222:225], v[0:3]
	v_mfma_f32_16x16x32_bf16 v[8:11], v[180:183], v[222:225], v[8:11]
	v_mfma_f32_16x16x32_bf16 v[8:11], v[176:179], v[218:221], v[8:11]
	s_barrier
	s_setprio 0
	s_add_i32 s75, s75, 2
	s_add_u32 s73, s73, 0x100
	s_addc_u32 s74, s74, 0
	s_add_u32 s46, s46, 0x100
	s_addc_u32 s47, s47, 0

.LBB0_531:
	v_add_u32_e32 v235, 0x84000, v235
	v_add_u32_e32 v234, 0x21800, v151
	ds_read_b128 v[236:239], v234
	ds_read_b128 v[240:243], v234 offset:256
	ds_read_b128 v[244:247], v234 offset:512
	ds_read_b128 v[248:251], v234 offset:768
	s_waitcnt lgkmcnt(0)
	v_add_f32_e32 v236, v236, v237
	v_add_f32_e32 v238, v238, v239
	v_add_f32_e32 v240, v240, v241
	v_add_f32_e32 v242, v242, v243
	v_add_f32_e32 v244, v244, v245
	v_add_f32_e32 v246, v246, v247
	v_add_f32_e32 v248, v248, v249
	v_add_f32_e32 v250, v250, v251
	v_add_f32_e32 v236, v236, v238
	v_add_f32_e32 v240, v240, v242
	v_add_f32_e32 v244, v244, v246
	v_add_f32_e32 v248, v248, v250
	v_fmamk_f32 v236, v236, 0x3a800000, v152
	v_fmamk_f32 v240, v240, 0x3a800000, v152
	v_fmamk_f32 v244, v244, 0x3a800000, v152
	v_fmamk_f32 v248, v248, 0x3a800000, v152
	v_rsq_f32_e32 v236, v236
	v_rsq_f32_e32 v240, v240
	v_rsq_f32_e32 v244, v244
	v_rsq_f32_e32 v248, v248
	v_mul_f32_e32 v252, 0xbfb8aa3b, v236
	v_mul_f32_e32 v254, v236, v236
	v_rcp_f32_e32 v254, v254
	v_pk_mul_f32 v[56:57], v[60:61], v[56:57]
	v_pk_mul_f32 v[58:59], v[62:63], v[58:59]
	v_pk_mul_f32 v[48:49], v[52:53], v[48:49]
	v_pk_mul_f32 v[50:51], v[54:55], v[50:51]
	v_pk_mul_f32 v[60:61], v[60:61], v[252:253] op_sel_hi:[1,0]
	v_pk_mul_f32 v[62:63], v[62:63], v[252:253] op_sel_hi:[1,0]
	v_pk_mul_f32 v[52:53], v[52:53], v[252:253] op_sel_hi:[1,0]
	v_pk_mul_f32 v[54:55], v[54:55], v[252:253] op_sel_hi:[1,0]
	v_exp_f32_e32 v60, v60
	v_exp_f32_e32 v61, v61
	v_exp_f32_e32 v62, v62
	v_exp_f32_e32 v63, v63
	v_exp_f32_e32 v52, v52
	v_exp_f32_e32 v53, v53
	v_exp_f32_e32 v54, v54
	v_exp_f32_e32 v55, v55
	v_pk_fma_f32 v[60:61], v[60:61], v[254:255], v[254:255] op_sel_hi:[1,0,0]
	v_pk_fma_f32 v[62:63], v[62:63], v[254:255], v[254:255] op_sel_hi:[1,0,0]
	v_pk_fma_f32 v[52:53], v[52:53], v[254:255], v[254:255] op_sel_hi:[1,0,0]
	v_pk_fma_f32 v[54:55], v[54:55], v[254:255], v[254:255] op_sel_hi:[1,0,0]
	v_mul_f32_e32 v238, v60, v61
	v_mul_f32_e32 v242, v62, v63
	v_mul_f32_e32 v246, v52, v53
	v_mul_f32_e32 v250, v54, v55
	v_rcp_f32_e32 v238, v238
	v_rcp_f32_e32 v242, v242
	v_rcp_f32_e32 v246, v246
	v_rcp_f32_e32 v250, v250
	v_pk_mul_f32 v[60:61], v[60:61], v[238:239] op_sel:[1,0] op_sel_hi:[0,0]
	v_pk_mul_f32 v[62:63], v[62:63], v[242:243] op_sel:[1,0] op_sel_hi:[0,0]
	v_pk_mul_f32 v[52:53], v[52:53], v[246:247] op_sel:[1,0] op_sel_hi:[0,0]
	v_pk_mul_f32 v[54:55], v[54:55], v[250:251] op_sel:[1,0] op_sel_hi:[0,0]
	v_pk_mul_f32 v[56:57], v[56:57], v[60:61]
	v_pk_mul_f32 v[58:59], v[58:59], v[62:63]
	v_pk_mul_f32 v[48:49], v[48:49], v[52:53]
	v_pk_mul_f32 v[50:51], v[50:51], v[54:55]
	v_cvt_pk_bf16_f32 v56, v56, v57
	v_cvt_pk_bf16_f32 v57, v58, v59
	v_cvt_pk_bf16_f32 v58, v48, v49
	v_cvt_pk_bf16_f32 v59, v50, v51
	global_store_dwordx4 v235, v[56:59], s[14:15]
	v_add_u32_e32 v234, 0x16000, v235
	v_mul_f32_e32 v252, 0xbfb8aa3b, v240
	v_mul_f32_e32 v254, v240, v240
	v_rcp_f32_e32 v254, v254
	v_pk_mul_f32 v[40:41], v[44:45], v[40:41]
	v_pk_mul_f32 v[42:43], v[46:47], v[42:43]
	v_pk_mul_f32 v[32:33], v[36:37], v[32:33]
	v_pk_mul_f32 v[34:35], v[38:39], v[34:35]
	v_pk_mul_f32 v[44:45], v[44:45], v[252:253] op_sel_hi:[1,0]
	v_pk_mul_f32 v[46:47], v[46:47], v[252:253] op_sel_hi:[1,0]
	v_pk_mul_f32 v[36:37], v[36:37], v[252:253] op_sel_hi:[1,0]
	v_pk_mul_f32 v[38:39], v[38:39], v[252:253] op_sel_hi:[1,0]
	v_exp_f32_e32 v44, v44
	v_exp_f32_e32 v45, v45
	v_exp_f32_e32 v46, v46
	v_exp_f32_e32 v47, v47
	v_exp_f32_e32 v36, v36
	v_exp_f32_e32 v37, v37
	v_exp_f32_e32 v38, v38
	v_exp_f32_e32 v39, v39
	v_pk_fma_f32 v[44:45], v[44:45], v[254:255], v[254:255] op_sel_hi:[1,0,0]
	v_pk_fma_f32 v[46:47], v[46:47], v[254:255], v[254:255] op_sel_hi:[1,0,0]
	v_pk_fma_f32 v[36:37], v[36:37], v[254:255], v[254:255] op_sel_hi:[1,0,0]
	v_pk_fma_f32 v[38:39], v[38:39], v[254:255], v[254:255] op_sel_hi:[1,0,0]
	v_mul_f32_e32 v238, v44, v45
	v_mul_f32_e32 v242, v46, v47
	v_mul_f32_e32 v246, v36, v37
	v_mul_f32_e32 v250, v38, v39
	v_rcp_f32_e32 v238, v238
	v_rcp_f32_e32 v242, v242
	v_rcp_f32_e32 v246, v246
	v_rcp_f32_e32 v250, v250
	v_pk_mul_f32 v[44:45], v[44:45], v[238:239] op_sel:[1,0] op_sel_hi:[0,0]
	v_pk_mul_f32 v[46:47], v[46:47], v[242:243] op_sel:[1,0] op_sel_hi:[0,0]
	v_pk_mul_f32 v[36:37], v[36:37], v[246:247] op_sel:[1,0] op_sel_hi:[0,0]
	v_pk_mul_f32 v[38:39], v[38:39], v[250:251] op_sel:[1,0] op_sel_hi:[0,0]
	v_pk_mul_f32 v[40:41], v[40:41], v[44:45]
	v_pk_mul_f32 v[42:43], v[42:43], v[46:47]
	v_pk_mul_f32 v[32:33], v[32:33], v[36:37]
	v_pk_mul_f32 v[34:35], v[34:35], v[38:39]
	v_cvt_pk_bf16_f32 v40, v40, v41
	v_cvt_pk_bf16_f32 v41, v42, v43
	v_cvt_pk_bf16_f32 v42, v32, v33
	v_cvt_pk_bf16_f32 v43, v34, v35
	global_store_dwordx4 v234, v[40:43], s[14:15]
	v_add_u32_e32 v235, 0x16000, v234
	v_mul_f32_e32 v252, 0xbfb8aa3b, v244
	v_mul_f32_e32 v254, v244, v244
	v_rcp_f32_e32 v254, v254
	v_pk_mul_f32 v[24:25], v[28:29], v[24:25]
	v_pk_mul_f32 v[26:27], v[30:31], v[26:27]
	v_pk_mul_f32 v[16:17], v[20:21], v[16:17]
	v_pk_mul_f32 v[18:19], v[22:23], v[18:19]
	v_pk_mul_f32 v[28:29], v[28:29], v[252:253] op_sel_hi:[1,0]
	v_pk_mul_f32 v[30:31], v[30:31], v[252:253] op_sel_hi:[1,0]
	v_pk_mul_f32 v[20:21], v[20:21], v[252:253] op_sel_hi:[1,0]
	v_pk_mul_f32 v[22:23], v[22:23], v[252:253] op_sel_hi:[1,0]
	v_exp_f32_e32 v28, v28
	v_exp_f32_e32 v29, v29
	v_exp_f32_e32 v30, v30
	v_exp_f32_e32 v31, v31
	v_exp_f32_e32 v20, v20
	v_exp_f32_e32 v21, v21
	v_exp_f32_e32 v22, v22
	v_exp_f32_e32 v23, v23
	v_pk_fma_f32 v[28:29], v[28:29], v[254:255], v[254:255] op_sel_hi:[1,0,0]
	v_pk_fma_f32 v[30:31], v[30:31], v[254:255], v[254:255] op_sel_hi:[1,0,0]
	v_pk_fma_f32 v[20:21], v[20:21], v[254:255], v[254:255] op_sel_hi:[1,0,0]
	v_pk_fma_f32 v[22:23], v[22:23], v[254:255], v[254:255] op_sel_hi:[1,0,0]
	v_mul_f32_e32 v238, v28, v29
	v_mul_f32_e32 v242, v30, v31
	v_mul_f32_e32 v246, v20, v21
	v_mul_f32_e32 v250, v22, v23
	v_rcp_f32_e32 v238, v238
	v_rcp_f32_e32 v242, v242
	v_rcp_f32_e32 v246, v246
	v_rcp_f32_e32 v250, v250
	v_pk_mul_f32 v[28:29], v[28:29], v[238:239] op_sel:[1,0] op_sel_hi:[0,0]
	v_pk_mul_f32 v[30:31], v[30:31], v[242:243] op_sel:[1,0] op_sel_hi:[0,0]
	v_pk_mul_f32 v[20:21], v[20:21], v[246:247] op_sel:[1,0] op_sel_hi:[0,0]
	v_pk_mul_f32 v[22:23], v[22:23], v[250:251] op_sel:[1,0] op_sel_hi:[0,0]
	v_pk_mul_f32 v[24:25], v[24:25], v[28:29]
	v_pk_mul_f32 v[26:27], v[26:27], v[30:31]
	v_pk_mul_f32 v[16:17], v[16:17], v[20:21]
	v_pk_mul_f32 v[18:19], v[18:19], v[22:23]
	v_cvt_pk_bf16_f32 v24, v24, v25
	v_cvt_pk_bf16_f32 v25, v26, v27
	v_cvt_pk_bf16_f32 v26, v16, v17
	v_cvt_pk_bf16_f32 v27, v18, v19
	global_store_dwordx4 v235, v[24:27], s[14:15]
	v_add_u32_e32 v234, 0x16000, v235
	v_mul_f32_e32 v252, 0xbfb8aa3b, v248
	v_mul_f32_e32 v254, v248, v248
	v_rcp_f32_e32 v254, v254
	v_pk_mul_f32 v[8:9], v[12:13], v[8:9]
	v_pk_mul_f32 v[10:11], v[14:15], v[10:11]
	v_pk_mul_f32 v[0:1], v[4:5], v[0:1]
	v_pk_mul_f32 v[2:3], v[6:7], v[2:3]
	v_pk_mul_f32 v[12:13], v[12:13], v[252:253] op_sel_hi:[1,0]
	v_pk_mul_f32 v[14:15], v[14:15], v[252:253] op_sel_hi:[1,0]
	v_pk_mul_f32 v[4:5], v[4:5], v[252:253] op_sel_hi:[1,0]
	v_pk_mul_f32 v[6:7], v[6:7], v[252:253] op_sel_hi:[1,0]
	v_exp_f32_e32 v12, v12
	v_exp_f32_e32 v13, v13
	v_exp_f32_e32 v14, v14
	v_exp_f32_e32 v15, v15
	v_exp_f32_e32 v4, v4
	v_exp_f32_e32 v5, v5
	v_exp_f32_e32 v6, v6
	v_exp_f32_e32 v7, v7
	v_pk_fma_f32 v[12:13], v[12:13], v[254:255], v[254:255] op_sel_hi:[1,0,0]
	v_pk_fma_f32 v[14:15], v[14:15], v[254:255], v[254:255] op_sel_hi:[1,0,0]
	v_pk_fma_f32 v[4:5], v[4:5], v[254:255], v[254:255] op_sel_hi:[1,0,0]
	v_pk_fma_f32 v[6:7], v[6:7], v[254:255], v[254:255] op_sel_hi:[1,0,0]
	v_mul_f32_e32 v238, v12, v13
	v_mul_f32_e32 v242, v14, v15
	v_mul_f32_e32 v246, v4, v5
	v_mul_f32_e32 v250, v6, v7
	v_rcp_f32_e32 v238, v238
	v_rcp_f32_e32 v242, v242
	v_rcp_f32_e32 v246, v246
	v_rcp_f32_e32 v250, v250
	v_pk_mul_f32 v[12:13], v[12:13], v[238:239] op_sel:[1,0] op_sel_hi:[0,0]
	v_pk_mul_f32 v[14:15], v[14:15], v[242:243] op_sel:[1,0] op_sel_hi:[0,0]
	v_pk_mul_f32 v[4:5], v[4:5], v[246:247] op_sel:[1,0] op_sel_hi:[0,0]
	v_pk_mul_f32 v[6:7], v[6:7], v[250:251] op_sel:[1,0] op_sel_hi:[0,0]
	v_pk_mul_f32 v[8:9], v[8:9], v[12:13]
	v_pk_mul_f32 v[10:11], v[10:11], v[14:15]
	v_pk_mul_f32 v[0:1], v[0:1], v[4:5]
	v_pk_mul_f32 v[2:3], v[2:3], v[6:7]
	v_cvt_pk_bf16_f32 v8, v8, v9
	v_cvt_pk_bf16_f32 v9, v10, v11
	v_cvt_pk_bf16_f32 v10, v0, v1
	v_cvt_pk_bf16_f32 v11, v2, v3
	global_store_dwordx4 v234, v[8:11], s[14:15]
	s_andn2_b64 vcc, exec, s[10:11]
	s_mov_b64 s[10:11], -1
	s_cbranch_vccnz .LBB0_522
	s_andn2_b64 vcc, exec, s[12:13]
	s_cbranch_vccnz .LBB0_521
	s_barrier
	s_branch .LBB0_521

.Llast_10:
	v_add_u32_e32 v153, s61, v147
	ds_read_b128 v[160:163], v153
	v_xor_b32_e32 v253, 64, v153
	ds_read_b128 v[164:167], v253
	ds_read_b128 v[168:171], v153 offset:2048
	ds_read_b128 v[172:175], v253 offset:2048
	v_add_u32_e32 v153, s62, v147
	ds_read_b128 v[176:179], v153
	v_xor_b32_e32 v253, 64, v153
	ds_read_b128 v[180:183], v253
	ds_read_b128 v[184:187], v153 offset:2048
	ds_read_b128 v[188:191], v253 offset:2048
	s_add_u32 s46, s30, 0xfffc0080
	s_addc_u32 s47, s31, -1
	s_and_b64 s[44:45], s[44:45], exec
	s_cselect_b32 s47, s25, s47
	s_cselect_b32 s46, s65, s46
	s_cselect_b32 s45, s66, s69
	s_cselect_b32 s44, s67, s68
	v_lshl_add_u64 v[154:155], s[30:31], 0, v[138:139]
	s_add_i32 m0, s52, 0xc000
	ds_read_b128 v[192:195], v150
	v_xor_b32_e32 v253, 64, v150
	ds_read_b128 v[196:199], v253
	ds_read_b128 v[200:203], v150 offset:2048
	ds_read_b128 v[204:207], v253 offset:2048
	ds_read_b128 v[208:211], v150 offset:4096
	ds_read_b128 v[212:215], v253 offset:4096
	ds_read_b128 v[216:219], v150 offset:6144
	ds_read_b128 v[220:223], v253 offset:6144
	global_load_lds_dwordx4 v[154:155], off
	v_lshl_add_u64 v[154:155], s[30:31], 0, v[136:137]
	s_add_i32 m0, s52, 0xe000
	s_nop 0
	global_load_lds_dwordx4 v[154:155], off
	s_waitcnt vmcnt(8)
	s_waitcnt lgkmcnt(0)
	s_setprio 1
	s_barrier
	v_mfma_f32_16x16x32_bf16 v[124:127], v[160:163], v[192:195], v[124:127]
	v_mfma_f32_16x16x32_bf16 v[124:127], v[164:167], v[196:199], v[124:127]
	v_mfma_f32_16x16x32_bf16 v[116:119], v[172:175], v[196:199], v[116:119]
	v_mfma_f32_16x16x32_bf16 v[116:119], v[168:171], v[192:195], v[116:119]
	v_mfma_f32_16x16x32_bf16 v[100:103], v[168:171], v[200:203], v[100:103]
	v_mfma_f32_16x16x32_bf16 v[100:103], v[172:175], v[204:207], v[100:103]
	v_mfma_f32_16x16x32_bf16 v[108:111], v[164:167], v[204:207], v[108:111]
	v_mfma_f32_16x16x32_bf16 v[108:111], v[160:163], v[200:203], v[108:111]
	v_mfma_f32_16x16x32_bf16 v[92:95], v[160:163], v[208:211], v[92:95]
	v_mfma_f32_16x16x32_bf16 v[92:95], v[164:167], v[212:215], v[92:95]
	v_mfma_f32_16x16x32_bf16 v[84:87], v[172:175], v[212:215], v[84:87]
	v_mfma_f32_16x16x32_bf16 v[84:87], v[168:171], v[208:211], v[84:87]
	v_mfma_f32_16x16x32_bf16 v[68:71], v[168:171], v[216:219], v[68:71]
	v_mfma_f32_16x16x32_bf16 v[68:71], v[172:175], v[220:223], v[68:71]
	v_mfma_f32_16x16x32_bf16 v[76:79], v[164:167], v[220:223], v[76:79]
	v_mfma_f32_16x16x32_bf16 v[76:79], v[160:163], v[216:219], v[76:79]
	s_setprio 0
	s_setprio 1
	v_mfma_f32_16x16x32_bf16 v[120:123], v[176:179], v[192:195], v[120:123]
	v_mfma_f32_16x16x32_bf16 v[120:123], v[180:183], v[196:199], v[120:123]
	v_mfma_f32_16x16x32_bf16 v[112:115], v[188:191], v[196:199], v[112:115]
	v_mfma_f32_16x16x32_bf16 v[112:115], v[184:187], v[192:195], v[112:115]
	v_mfma_f32_16x16x32_bf16 v[96:99], v[184:187], v[200:203], v[96:99]
	v_mfma_f32_16x16x32_bf16 v[96:99], v[188:191], v[204:207], v[96:99]
	v_mfma_f32_16x16x32_bf16 v[104:107], v[180:183], v[204:207], v[104:107]
	v_mfma_f32_16x16x32_bf16 v[104:107], v[176:179], v[200:203], v[104:107]
	v_mfma_f32_16x16x32_bf16 v[88:91], v[176:179], v[208:211], v[88:91]
	v_mfma_f32_16x16x32_bf16 v[88:91], v[180:183], v[212:215], v[88:91]
	v_mfma_f32_16x16x32_bf16 v[80:83], v[188:191], v[212:215], v[80:83]
	v_mfma_f32_16x16x32_bf16 v[80:83], v[184:187], v[208:211], v[80:83]
	v_mfma_f32_16x16x32_bf16 v[64:67], v[184:187], v[216:219], v[64:67]
	v_mfma_f32_16x16x32_bf16 v[64:67], v[188:191], v[220:223], v[64:67]
	v_mfma_f32_16x16x32_bf16 v[72:75], v[180:183], v[220:223], v[72:75]
	v_mfma_f32_16x16x32_bf16 v[72:75], v[176:179], v[216:219], v[72:75]
	s_barrier
	s_setprio 0
	s_add_i32 s71, s61, s49
	v_lshl_add_u64 v[154:155], s[44:45], 0, v[132:133]
	s_mov_b32 m0, s71
	ds_read_b128 v[192:195], v150 offset:16384
	v_xor_b32_e32 v253, 64, v150
	ds_read_b128 v[196:199], v253 offset:16384
	ds_read_b128 v[200:203], v150 offset:18432
	ds_read_b128 v[204:207], v253 offset:18432
	ds_read_b128 v[208:211], v150 offset:20480
	ds_read_b128 v[212:215], v253 offset:20480
	ds_read_b128 v[216:219], v150 offset:22528
	ds_read_b128 v[220:223], v253 offset:22528
	global_load_lds_dwordx4 v[154:155], off
	s_add_i32 m0, s71, 0x2000
	s_add_u32 s72, s44, 0x40000
	v_lshl_add_u64 v[224:225], s[44:45], 0, v[128:129]
	s_addc_u32 s73, s45, 0
	s_add_i32 s71, s62, s49
	global_load_lds_dwordx4 v[224:225], off
	v_lshl_add_u64 v[226:227], s[72:73], 0, v[132:133]
	s_mov_b32 m0, s71
	v_lshl_add_u64 v[228:229], s[46:47], 0, v[130:131]
	global_load_lds_dwordx4 v[226:227], off
	v_lshl_add_u64 v[226:227], s[72:73], 0, v[128:129]
	s_add_i32 m0, s71, 0x2000
	s_nop 0
	global_load_lds_dwordx4 v[226:227], off
	v_lshl_add_u64 v[226:227], s[46:47], 0, v[134:135]
	s_mov_b32 m0, s52
	s_nop 0
	global_load_lds_dwordx4 v[226:227], off
	s_mov_b32 m0, s53
	s_nop 0
	global_load_lds_dwordx4 v[228:229], off
	s_waitcnt vmcnt(8)
	s_waitcnt lgkmcnt(0)
	s_setprio 1
	s_barrier
	v_mfma_f32_16x16x32_bf16 v[60:63], v[160:163], v[192:195], v[60:63]
	v_mfma_f32_16x16x32_bf16 v[60:63], v[164:167], v[196:199], v[60:63]
	v_mfma_f32_16x16x32_bf16 v[52:55], v[172:175], v[196:199], v[52:55]
	v_mfma_f32_16x16x32_bf16 v[52:55], v[168:171], v[192:195], v[52:55]
	v_mfma_f32_16x16x32_bf16 v[36:39], v[168:171], v[200:203], v[36:39]
	v_mfma_f32_16x16x32_bf16 v[36:39], v[172:175], v[204:207], v[36:39]
	v_mfma_f32_16x16x32_bf16 v[44:47], v[164:167], v[204:207], v[44:47]
	v_mfma_f32_16x16x32_bf16 v[44:47], v[160:163], v[200:203], v[44:47]
	v_mfma_f32_16x16x32_bf16 v[28:31], v[160:163], v[208:211], v[28:31]
	v_mfma_f32_16x16x32_bf16 v[28:31], v[164:167], v[212:215], v[28:31]
	v_mfma_f32_16x16x32_bf16 v[20:23], v[172:175], v[212:215], v[20:23]
	v_mfma_f32_16x16x32_bf16 v[20:23], v[168:171], v[208:211], v[20:23]
	v_mfma_f32_16x16x32_bf16 v[4:7], v[168:171], v[216:219], v[4:7]
	v_mfma_f32_16x16x32_bf16 v[4:7], v[172:175], v[220:223], v[4:7]
	v_mfma_f32_16x16x32_bf16 v[12:15], v[164:167], v[220:223], v[12:15]
	v_mfma_f32_16x16x32_bf16 v[12:15], v[160:163], v[216:219], v[12:15]
	s_setprio 0
	s_setprio 1
	v_mfma_f32_16x16x32_bf16 v[56:59], v[176:179], v[192:195], v[56:59]
	v_mfma_f32_16x16x32_bf16 v[56:59], v[180:183], v[196:199], v[56:59]
	v_mfma_f32_16x16x32_bf16 v[48:51], v[188:191], v[196:199], v[48:51]
	v_mfma_f32_16x16x32_bf16 v[48:51], v[184:187], v[192:195], v[48:51]
	v_mfma_f32_16x16x32_bf16 v[32:35], v[184:187], v[200:203], v[32:35]
	v_mfma_f32_16x16x32_bf16 v[32:35], v[188:191], v[204:207], v[32:35]
	v_mfma_f32_16x16x32_bf16 v[40:43], v[180:183], v[204:207], v[40:43]
	v_mfma_f32_16x16x32_bf16 v[40:43], v[176:179], v[200:203], v[40:43]
	v_mfma_f32_16x16x32_bf16 v[24:27], v[176:179], v[208:211], v[24:27]
	v_mfma_f32_16x16x32_bf16 v[24:27], v[180:183], v[212:215], v[24:27]
	v_mfma_f32_16x16x32_bf16 v[16:19], v[188:191], v[212:215], v[16:19]
	v_mfma_f32_16x16x32_bf16 v[16:19], v[184:187], v[208:211], v[16:19]
	v_mfma_f32_16x16x32_bf16 v[0:3], v[184:187], v[216:219], v[0:3]
	v_mfma_f32_16x16x32_bf16 v[0:3], v[188:191], v[220:223], v[0:3]
	v_mfma_f32_16x16x32_bf16 v[8:11], v[180:183], v[220:223], v[8:11]
	v_mfma_f32_16x16x32_bf16 v[8:11], v[176:179], v[216:219], v[8:11]
	s_barrier
	s_setprio 0
	s_add_i32 s71, 0, 0x18000
	v_add_u32_e32 v153, s71, v147
	s_add_i32 s72, 0, 0x1c000
	ds_read_b128 v[160:163], v153
	v_xor_b32_e32 v253, 64, v153
	ds_read_b128 v[164:167], v253
	ds_read_b128 v[168:171], v153 offset:2048
	ds_read_b128 v[172:175], v253 offset:2048
	v_add_u32_e32 v153, s72, v147
	ds_read_b128 v[176:179], v153
	v_xor_b32_e32 v253, 64, v153
	ds_read_b128 v[180:183], v253
	ds_read_b128 v[184:187], v153 offset:2048
	ds_read_b128 v[188:191], v253 offset:2048
	s_add_u32 s46, s46, 0x40000
	s_addc_u32 s47, s47, 0
	s_mov_b32 m0, s54
	v_lshl_add_u64 v[230:231], s[46:47], 0, v[134:135]
	ds_read_b128 v[192:195], v150 offset:32768
	v_xor_b32_e32 v253, 64, v150
	ds_read_b128 v[196:199], v253 offset:32768
	ds_read_b128 v[200:203], v150 offset:34816
	ds_read_b128 v[204:207], v253 offset:34816
	ds_read_b128 v[208:211], v150 offset:36864
	ds_read_b128 v[212:215], v253 offset:36864
	ds_read_b128 v[216:219], v150 offset:38912
	ds_read_b128 v[220:223], v253 offset:38912
	global_load_lds_dwordx4 v[230:231], off
	v_lshl_add_u64 v[230:231], s[46:47], 0, v[130:131]
	s_mov_b32 m0, s55
	s_nop 0
	global_load_lds_dwordx4 v[230:231], off
	s_waitcnt vmcnt(8)
	s_waitcnt lgkmcnt(0)
	s_setprio 1
	s_barrier
	v_mfma_f32_16x16x32_bf16 v[124:127], v[160:163], v[192:195], v[124:127]
	v_mfma_f32_16x16x32_bf16 v[124:127], v[164:167], v[196:199], v[124:127]
	v_mfma_f32_16x16x32_bf16 v[116:119], v[172:175], v[196:199], v[116:119]
	v_mfma_f32_16x16x32_bf16 v[116:119], v[168:171], v[192:195], v[116:119]
	v_mfma_f32_16x16x32_bf16 v[100:103], v[168:171], v[200:203], v[100:103]
	v_mfma_f32_16x16x32_bf16 v[100:103], v[172:175], v[204:207], v[100:103]
	v_mfma_f32_16x16x32_bf16 v[108:111], v[164:167], v[204:207], v[108:111]
	v_mfma_f32_16x16x32_bf16 v[108:111], v[160:163], v[200:203], v[108:111]
	v_mfma_f32_16x16x32_bf16 v[92:95], v[160:163], v[208:211], v[92:95]
	v_mfma_f32_16x16x32_bf16 v[92:95], v[164:167], v[212:215], v[92:95]
	v_mfma_f32_16x16x32_bf16 v[84:87], v[172:175], v[212:215], v[84:87]
	v_mfma_f32_16x16x32_bf16 v[84:87], v[168:171], v[208:211], v[84:87]
	v_mfma_f32_16x16x32_bf16 v[68:71], v[168:171], v[216:219], v[68:71]
	v_mfma_f32_16x16x32_bf16 v[68:71], v[172:175], v[220:223], v[68:71]
	v_mfma_f32_16x16x32_bf16 v[76:79], v[164:167], v[220:223], v[76:79]
	v_mfma_f32_16x16x32_bf16 v[76:79], v[160:163], v[216:219], v[76:79]
	s_setprio 0
	s_setprio 1
	v_mfma_f32_16x16x32_bf16 v[120:123], v[176:179], v[192:195], v[120:123]
	v_mfma_f32_16x16x32_bf16 v[120:123], v[180:183], v[196:199], v[120:123]
	v_mfma_f32_16x16x32_bf16 v[112:115], v[188:191], v[196:199], v[112:115]
	v_mfma_f32_16x16x32_bf16 v[112:115], v[184:187], v[192:195], v[112:115]
	v_mfma_f32_16x16x32_bf16 v[96:99], v[184:187], v[200:203], v[96:99]
	v_mfma_f32_16x16x32_bf16 v[96:99], v[188:191], v[204:207], v[96:99]
	v_mfma_f32_16x16x32_bf16 v[104:107], v[180:183], v[204:207], v[104:107]
	v_mfma_f32_16x16x32_bf16 v[104:107], v[176:179], v[200:203], v[104:107]
	v_mfma_f32_16x16x32_bf16 v[88:91], v[176:179], v[208:211], v[88:91]
	v_mfma_f32_16x16x32_bf16 v[88:91], v[180:183], v[212:215], v[88:91]
	v_mfma_f32_16x16x32_bf16 v[80:83], v[188:191], v[212:215], v[80:83]
	v_mfma_f32_16x16x32_bf16 v[80:83], v[184:187], v[208:211], v[80:83]
	v_mfma_f32_16x16x32_bf16 v[64:67], v[184:187], v[216:219], v[64:67]
	v_mfma_f32_16x16x32_bf16 v[64:67], v[188:191], v[220:223], v[64:67]
	v_mfma_f32_16x16x32_bf16 v[72:75], v[180:183], v[220:223], v[72:75]
	v_mfma_f32_16x16x32_bf16 v[72:75], v[176:179], v[216:219], v[72:75]
	s_barrier
	s_setprio 0
	v_add_u32_e32 v234, 0x21000, v151
	ds_read_b128 v[236:239], v234
	ds_read_b128 v[240:243], v234 offset:256
	ds_read_b128 v[244:247], v234 offset:512
	ds_read_b128 v[248:251], v234 offset:768
	v_add_u32_e32 v235, s23, v146
	v_mul_u32_u24_e32 v235, 0x1600, v235
	v_lshl_or_b32 v234, s64, 7, v149
	v_lshl_add_u32 v235, v234, 1, v235
	s_add_i32 s46, s71, s49
	v_lshl_add_u64 v[154:155], v[154:155], 0, s[14:15]
	s_mov_b32 m0, s46
	ds_read_b128 v[192:195], v150 offset:49152
	v_xor_b32_e32 v253, 64, v150
	ds_read_b128 v[196:199], v253 offset:49152
	ds_read_b128 v[200:203], v150 offset:51200
	ds_read_b128 v[204:207], v253 offset:51200
	ds_read_b128 v[208:211], v150 offset:53248
	ds_read_b128 v[212:215], v253 offset:53248
	ds_read_b128 v[216:219], v150 offset:55296
	ds_read_b128 v[220:223], v253 offset:55296
	global_load_lds_dwordx4 v[154:155], off
	s_add_i32 m0, s46, 0x2000
	s_add_u32 s44, s44, 0x40080
	v_lshl_add_u64 v[154:155], v[224:225], 0, s[14:15]
	s_addc_u32 s45, s45, 0
	s_add_i32 s46, s72, s49
	global_load_lds_dwordx4 v[154:155], off
	v_lshl_add_u64 v[154:155], s[44:45], 0, v[132:133]
	s_mov_b32 m0, s46
	s_nop 0
	global_load_lds_dwordx4 v[154:155], off
	v_lshl_add_u64 v[154:155], s[44:45], 0, v[128:129]
	s_add_i32 m0, s46, 0x2000
	s_nop 0
	global_load_lds_dwordx4 v[154:155], off
	v_lshl_add_u64 v[154:155], v[226:227], 0, s[14:15]
	s_mov_b32 m0, s57
	s_nop 0
	global_load_lds_dwordx4 v[154:155], off
	v_lshl_add_u64 v[154:155], v[228:229], 0, s[14:15]
	s_mov_b32 m0, s58
	s_nop 0
	global_load_lds_dwordx4 v[154:155], off
	s_waitcnt lgkmcnt(8)
	v_add_f32_e32 v236, v236, v237
	v_add_f32_e32 v238, v238, v239
	v_add_f32_e32 v240, v240, v241
	v_add_f32_e32 v242, v242, v243
	v_add_f32_e32 v244, v244, v245
	v_add_f32_e32 v246, v246, v247
	v_add_f32_e32 v248, v248, v249
	v_add_f32_e32 v250, v250, v251
	v_add_f32_e32 v236, v236, v238
	v_add_f32_e32 v240, v240, v242
	v_add_f32_e32 v244, v244, v246
	v_add_f32_e32 v248, v248, v250
	v_fmamk_f32 v236, v236, 0x3a800000, v152
	v_fmamk_f32 v240, v240, 0x3a800000, v152
	v_fmamk_f32 v244, v244, 0x3a800000, v152
	v_fmamk_f32 v248, v248, 0x3a800000, v152
	v_rsq_f32_e32 v236, v236
	v_rsq_f32_e32 v240, v240
	v_rsq_f32_e32 v244, v244
	v_rsq_f32_e32 v248, v248
	v_mul_f32_e32 v252, 0xbfb8aa3b, v236
	v_mul_f32_e32 v254, v236, v236
	v_rcp_f32_e32 v254, v254
	v_pk_mul_f32 v[120:121], v[124:125], v[120:121]
	v_pk_mul_f32 v[122:123], v[126:127], v[122:123]
	v_pk_mul_f32 v[112:113], v[116:117], v[112:113]
	v_pk_mul_f32 v[114:115], v[118:119], v[114:115]
	v_pk_mul_f32 v[124:125], v[124:125], v[252:253] op_sel_hi:[1,0]
	v_pk_mul_f32 v[126:127], v[126:127], v[252:253] op_sel_hi:[1,0]
	v_pk_mul_f32 v[116:117], v[116:117], v[252:253] op_sel_hi:[1,0]
	v_pk_mul_f32 v[118:119], v[118:119], v[252:253] op_sel_hi:[1,0]
	v_exp_f32_e32 v124, v124
	v_exp_f32_e32 v125, v125
	v_exp_f32_e32 v126, v126
	v_exp_f32_e32 v127, v127
	v_exp_f32_e32 v116, v116
	v_exp_f32_e32 v117, v117
	v_exp_f32_e32 v118, v118
	v_exp_f32_e32 v119, v119
	v_pk_fma_f32 v[124:125], v[124:125], v[254:255], v[254:255] op_sel_hi:[1,0,0]
	v_pk_fma_f32 v[126:127], v[126:127], v[254:255], v[254:255] op_sel_hi:[1,0,0]
	v_pk_fma_f32 v[116:117], v[116:117], v[254:255], v[254:255] op_sel_hi:[1,0,0]
	v_pk_fma_f32 v[118:119], v[118:119], v[254:255], v[254:255] op_sel_hi:[1,0,0]
	v_mul_f32_e32 v238, v124, v125
	v_mul_f32_e32 v242, v126, v127
	v_mul_f32_e32 v246, v116, v117
	v_mul_f32_e32 v250, v118, v119
	v_rcp_f32_e32 v238, v238
	v_rcp_f32_e32 v242, v242
	v_rcp_f32_e32 v246, v246
	v_rcp_f32_e32 v250, v250
	v_pk_mul_f32 v[124:125], v[124:125], v[238:239] op_sel:[1,0] op_sel_hi:[0,0]
	v_pk_mul_f32 v[126:127], v[126:127], v[242:243] op_sel:[1,0] op_sel_hi:[0,0]
	v_pk_mul_f32 v[116:117], v[116:117], v[246:247] op_sel:[1,0] op_sel_hi:[0,0]
	v_pk_mul_f32 v[118:119], v[118:119], v[250:251] op_sel:[1,0] op_sel_hi:[0,0]
	v_pk_mul_f32 v[120:121], v[120:121], v[124:125]
	v_pk_mul_f32 v[122:123], v[122:123], v[126:127]
	v_pk_mul_f32 v[112:113], v[112:113], v[116:117]
	v_pk_mul_f32 v[114:115], v[114:115], v[118:119]
	v_cvt_pk_bf16_f32 v120, v120, v121
	v_cvt_pk_bf16_f32 v121, v122, v123
	v_cvt_pk_bf16_f32 v122, v112, v113
	v_cvt_pk_bf16_f32 v123, v114, v115
	global_store_dwordx4 v235, v[120:123], s[10:11]
	v_add_u32_e32 v234, 0x16000, v235
	v_mul_f32_e32 v252, 0xbfb8aa3b, v240
	v_mul_f32_e32 v254, v240, v240
	v_rcp_f32_e32 v254, v254
	v_pk_mul_f32 v[104:105], v[108:109], v[104:105]
	v_pk_mul_f32 v[106:107], v[110:111], v[106:107]
	v_pk_mul_f32 v[96:97], v[100:101], v[96:97]
	v_pk_mul_f32 v[98:99], v[102:103], v[98:99]
	v_pk_mul_f32 v[108:109], v[108:109], v[252:253] op_sel_hi:[1,0]
	v_pk_mul_f32 v[110:111], v[110:111], v[252:253] op_sel_hi:[1,0]
	v_pk_mul_f32 v[100:101], v[100:101], v[252:253] op_sel_hi:[1,0]
	v_pk_mul_f32 v[102:103], v[102:103], v[252:253] op_sel_hi:[1,0]
	v_exp_f32_e32 v108, v108
	v_exp_f32_e32 v109, v109
	v_exp_f32_e32 v110, v110
	v_exp_f32_e32 v111, v111
	v_exp_f32_e32 v100, v100
	v_exp_f32_e32 v101, v101
	v_exp_f32_e32 v102, v102
	v_exp_f32_e32 v103, v103
	v_pk_fma_f32 v[108:109], v[108:109], v[254:255], v[254:255] op_sel_hi:[1,0,0]
	v_pk_fma_f32 v[110:111], v[110:111], v[254:255], v[254:255] op_sel_hi:[1,0,0]
	v_pk_fma_f32 v[100:101], v[100:101], v[254:255], v[254:255] op_sel_hi:[1,0,0]
	v_pk_fma_f32 v[102:103], v[102:103], v[254:255], v[254:255] op_sel_hi:[1,0,0]
	v_mul_f32_e32 v238, v108, v109
	v_mul_f32_e32 v242, v110, v111
	v_mul_f32_e32 v246, v100, v101
	v_mul_f32_e32 v250, v102, v103
	v_rcp_f32_e32 v238, v238
	v_rcp_f32_e32 v242, v242
	v_rcp_f32_e32 v246, v246
	v_rcp_f32_e32 v250, v250
	v_pk_mul_f32 v[108:109], v[108:109], v[238:239] op_sel:[1,0] op_sel_hi:[0,0]
	v_pk_mul_f32 v[110:111], v[110:111], v[242:243] op_sel:[1,0] op_sel_hi:[0,0]
	v_pk_mul_f32 v[100:101], v[100:101], v[246:247] op_sel:[1,0] op_sel_hi:[0,0]
	v_pk_mul_f32 v[102:103], v[102:103], v[250:251] op_sel:[1,0] op_sel_hi:[0,0]
	v_pk_mul_f32 v[104:105], v[104:105], v[108:109]
	v_pk_mul_f32 v[106:107], v[106:107], v[110:111]
	v_pk_mul_f32 v[96:97], v[96:97], v[100:101]
	v_pk_mul_f32 v[98:99], v[98:99], v[102:103]
	v_cvt_pk_bf16_f32 v104, v104, v105
	v_cvt_pk_bf16_f32 v105, v106, v107
	v_cvt_pk_bf16_f32 v106, v96, v97
	v_cvt_pk_bf16_f32 v107, v98, v99
	global_store_dwordx4 v234, v[104:107], s[10:11]
	v_add_u32_e32 v235, 0x16000, v234
	v_mul_f32_e32 v252, 0xbfb8aa3b, v244
	v_mul_f32_e32 v254, v244, v244
	v_rcp_f32_e32 v254, v254
	v_pk_mul_f32 v[88:89], v[92:93], v[88:89]
	v_pk_mul_f32 v[90:91], v[94:95], v[90:91]
	v_pk_mul_f32 v[80:81], v[84:85], v[80:81]
	v_pk_mul_f32 v[82:83], v[86:87], v[82:83]
	v_pk_mul_f32 v[92:93], v[92:93], v[252:253] op_sel_hi:[1,0]
	v_pk_mul_f32 v[94:95], v[94:95], v[252:253] op_sel_hi:[1,0]
	v_pk_mul_f32 v[84:85], v[84:85], v[252:253] op_sel_hi:[1,0]
	v_pk_mul_f32 v[86:87], v[86:87], v[252:253] op_sel_hi:[1,0]
	v_exp_f32_e32 v92, v92
	v_exp_f32_e32 v93, v93
	v_exp_f32_e32 v94, v94
	v_exp_f32_e32 v95, v95
	v_exp_f32_e32 v84, v84
	v_exp_f32_e32 v85, v85
	v_exp_f32_e32 v86, v86
	v_exp_f32_e32 v87, v87
	v_pk_fma_f32 v[92:93], v[92:93], v[254:255], v[254:255] op_sel_hi:[1,0,0]
	v_pk_fma_f32 v[94:95], v[94:95], v[254:255], v[254:255] op_sel_hi:[1,0,0]
	v_pk_fma_f32 v[84:85], v[84:85], v[254:255], v[254:255] op_sel_hi:[1,0,0]
	v_pk_fma_f32 v[86:87], v[86:87], v[254:255], v[254:255] op_sel_hi:[1,0,0]
	v_mul_f32_e32 v238, v92, v93
	v_mul_f32_e32 v242, v94, v95
	v_mul_f32_e32 v246, v84, v85
	v_mul_f32_e32 v250, v86, v87
	v_rcp_f32_e32 v238, v238
	v_rcp_f32_e32 v242, v242
	v_rcp_f32_e32 v246, v246
	v_rcp_f32_e32 v250, v250
	v_pk_mul_f32 v[92:93], v[92:93], v[238:239] op_sel:[1,0] op_sel_hi:[0,0]
	v_pk_mul_f32 v[94:95], v[94:95], v[242:243] op_sel:[1,0] op_sel_hi:[0,0]
	v_pk_mul_f32 v[84:85], v[84:85], v[246:247] op_sel:[1,0] op_sel_hi:[0,0]
	v_pk_mul_f32 v[86:87], v[86:87], v[250:251] op_sel:[1,0] op_sel_hi:[0,0]
	v_pk_mul_f32 v[88:89], v[88:89], v[92:93]
	v_pk_mul_f32 v[90:91], v[90:91], v[94:95]
	v_pk_mul_f32 v[80:81], v[80:81], v[84:85]
	v_pk_mul_f32 v[82:83], v[82:83], v[86:87]
	v_cvt_pk_bf16_f32 v88, v88, v89
	v_cvt_pk_bf16_f32 v89, v90, v91
	v_cvt_pk_bf16_f32 v90, v80, v81
	v_cvt_pk_bf16_f32 v91, v82, v83
	global_store_dwordx4 v235, v[88:91], s[10:11]
	v_add_u32_e32 v234, 0x16000, v235
	v_mul_f32_e32 v252, 0xbfb8aa3b, v248
	v_mul_f32_e32 v254, v248, v248
	v_rcp_f32_e32 v254, v254
	v_pk_mul_f32 v[72:73], v[76:77], v[72:73]
	v_pk_mul_f32 v[74:75], v[78:79], v[74:75]
	v_pk_mul_f32 v[64:65], v[68:69], v[64:65]
	v_pk_mul_f32 v[66:67], v[70:71], v[66:67]
	v_pk_mul_f32 v[76:77], v[76:77], v[252:253] op_sel_hi:[1,0]
	v_pk_mul_f32 v[78:79], v[78:79], v[252:253] op_sel_hi:[1,0]
	v_pk_mul_f32 v[68:69], v[68:69], v[252:253] op_sel_hi:[1,0]
	v_pk_mul_f32 v[70:71], v[70:71], v[252:253] op_sel_hi:[1,0]
	v_exp_f32_e32 v76, v76
	v_exp_f32_e32 v77, v77
	v_exp_f32_e32 v78, v78
	v_exp_f32_e32 v79, v79
	v_exp_f32_e32 v68, v68
	v_exp_f32_e32 v69, v69
	v_exp_f32_e32 v70, v70
	v_exp_f32_e32 v71, v71
	v_pk_fma_f32 v[76:77], v[76:77], v[254:255], v[254:255] op_sel_hi:[1,0,0]
	v_pk_fma_f32 v[78:79], v[78:79], v[254:255], v[254:255] op_sel_hi:[1,0,0]
	v_pk_fma_f32 v[68:69], v[68:69], v[254:255], v[254:255] op_sel_hi:[1,0,0]
	v_pk_fma_f32 v[70:71], v[70:71], v[254:255], v[254:255] op_sel_hi:[1,0,0]
	v_mul_f32_e32 v238, v76, v77
	v_mul_f32_e32 v242, v78, v79
	v_mul_f32_e32 v246, v68, v69
	v_mul_f32_e32 v250, v70, v71
	v_rcp_f32_e32 v238, v238
	v_rcp_f32_e32 v242, v242
	v_rcp_f32_e32 v246, v246
	v_rcp_f32_e32 v250, v250
	v_pk_mul_f32 v[76:77], v[76:77], v[238:239] op_sel:[1,0] op_sel_hi:[0,0]
	v_pk_mul_f32 v[78:79], v[78:79], v[242:243] op_sel:[1,0] op_sel_hi:[0,0]
	v_pk_mul_f32 v[68:69], v[68:69], v[246:247] op_sel:[1,0] op_sel_hi:[0,0]
	v_pk_mul_f32 v[70:71], v[70:71], v[250:251] op_sel:[1,0] op_sel_hi:[0,0]
	v_pk_mul_f32 v[72:73], v[72:73], v[76:77]
	v_pk_mul_f32 v[74:75], v[74:75], v[78:79]
	v_pk_mul_f32 v[64:65], v[64:65], v[68:69]
	v_pk_mul_f32 v[66:67], v[66:67], v[70:71]
	v_cvt_pk_bf16_f32 v72, v72, v73
	v_cvt_pk_bf16_f32 v73, v74, v75
	v_cvt_pk_bf16_f32 v74, v64, v65
	v_cvt_pk_bf16_f32 v75, v66, v67
	global_store_dwordx4 v234, v[72:75], s[10:11]
	s_waitcnt vmcnt(12)
	s_waitcnt lgkmcnt(0)
	s_setprio 1
	s_barrier
	v_mfma_f32_16x16x32_bf16 v[60:63], v[160:163], v[192:195], v[60:63]
	v_mfma_f32_16x16x32_bf16 v[60:63], v[164:167], v[196:199], v[60:63]
	v_mfma_f32_16x16x32_bf16 v[52:55], v[172:175], v[196:199], v[52:55]
	v_mfma_f32_16x16x32_bf16 v[52:55], v[168:171], v[192:195], v[52:55]
	v_mfma_f32_16x16x32_bf16 v[36:39], v[168:171], v[200:203], v[36:39]
	v_mfma_f32_16x16x32_bf16 v[36:39], v[172:175], v[204:207], v[36:39]
	v_mfma_f32_16x16x32_bf16 v[44:47], v[164:167], v[204:207], v[44:47]
	v_mfma_f32_16x16x32_bf16 v[44:47], v[160:163], v[200:203], v[44:47]
	v_mfma_f32_16x16x32_bf16 v[28:31], v[160:163], v[208:211], v[28:31]
	v_mfma_f32_16x16x32_bf16 v[28:31], v[164:167], v[212:215], v[28:31]
	v_mfma_f32_16x16x32_bf16 v[20:23], v[172:175], v[212:215], v[20:23]
	v_mfma_f32_16x16x32_bf16 v[20:23], v[168:171], v[208:211], v[20:23]
	v_mfma_f32_16x16x32_bf16 v[4:7], v[168:171], v[216:219], v[4:7]
	v_mfma_f32_16x16x32_bf16 v[4:7], v[172:175], v[220:223], v[4:7]
	v_mfma_f32_16x16x32_bf16 v[12:15], v[164:167], v[220:223], v[12:15]
	v_mfma_f32_16x16x32_bf16 v[12:15], v[160:163], v[216:219], v[12:15]
	s_setprio 0
	s_setprio 1
	v_mfma_f32_16x16x32_bf16 v[56:59], v[176:179], v[192:195], v[56:59]
	v_mfma_f32_16x16x32_bf16 v[56:59], v[180:183], v[196:199], v[56:59]
	v_mfma_f32_16x16x32_bf16 v[48:51], v[188:191], v[196:199], v[48:51]
	v_mfma_f32_16x16x32_bf16 v[48:51], v[184:187], v[192:195], v[48:51]
	v_mfma_f32_16x16x32_bf16 v[32:35], v[184:187], v[200:203], v[32:35]
	v_mfma_f32_16x16x32_bf16 v[32:35], v[188:191], v[204:207], v[32:35]
	v_mfma_f32_16x16x32_bf16 v[40:43], v[180:183], v[204:207], v[40:43]
	v_mfma_f32_16x16x32_bf16 v[40:43], v[176:179], v[200:203], v[40:43]
	v_mfma_f32_16x16x32_bf16 v[24:27], v[176:179], v[208:211], v[24:27]
	v_mfma_f32_16x16x32_bf16 v[24:27], v[180:183], v[212:215], v[24:27]
	v_mfma_f32_16x16x32_bf16 v[16:19], v[188:191], v[212:215], v[16:19]
	v_mfma_f32_16x16x32_bf16 v[16:19], v[184:187], v[208:211], v[16:19]
	v_mfma_f32_16x16x32_bf16 v[0:3], v[184:187], v[216:219], v[0:3]
	v_mfma_f32_16x16x32_bf16 v[0:3], v[188:191], v[220:223], v[0:3]
	v_mfma_f32_16x16x32_bf16 v[8:11], v[180:183], v[220:223], v[8:11]
	v_mfma_f32_16x16x32_bf16 v[8:11], v[176:179], v[216:219], v[8:11]
	s_barrier
	s_setprio 0
	s_add_i32 s70, s70, 2
	s_add_u32 s68, s68, 0x100
	s_addc_u32 s69, s69, 0
	s_add_u32 s30, s30, 0x100
	s_addc_u32 s31, s31, 0

.LBB0_1102:
	v_add_u32_e32 v235, 0x84000, v235
	v_add_u32_e32 v234, 0x21800, v151
	ds_read_b128 v[236:239], v234
	ds_read_b128 v[240:243], v234 offset:256
	ds_read_b128 v[244:247], v234 offset:512
	ds_read_b128 v[248:251], v234 offset:768
	s_waitcnt lgkmcnt(0)
	v_add_f32_e32 v236, v236, v237
	v_add_f32_e32 v238, v238, v239
	v_add_f32_e32 v240, v240, v241
	v_add_f32_e32 v242, v242, v243
	v_add_f32_e32 v244, v244, v245
	v_add_f32_e32 v246, v246, v247
	v_add_f32_e32 v248, v248, v249
	v_add_f32_e32 v250, v250, v251
	v_add_f32_e32 v236, v236, v238
	v_add_f32_e32 v240, v240, v242
	v_add_f32_e32 v244, v244, v246
	v_add_f32_e32 v248, v248, v250
	v_fmamk_f32 v236, v236, 0x3a800000, v152
	v_fmamk_f32 v240, v240, 0x3a800000, v152
	v_fmamk_f32 v244, v244, 0x3a800000, v152
	v_fmamk_f32 v248, v248, 0x3a800000, v152
	v_rsq_f32_e32 v236, v236
	v_rsq_f32_e32 v240, v240
	v_rsq_f32_e32 v244, v244
	v_rsq_f32_e32 v248, v248
	v_mul_f32_e32 v252, 0xbfb8aa3b, v236
	v_mul_f32_e32 v254, v236, v236
	v_rcp_f32_e32 v254, v254
	v_pk_mul_f32 v[56:57], v[60:61], v[56:57]
	v_pk_mul_f32 v[58:59], v[62:63], v[58:59]
	v_pk_mul_f32 v[48:49], v[52:53], v[48:49]
	v_pk_mul_f32 v[50:51], v[54:55], v[50:51]
	v_pk_mul_f32 v[60:61], v[60:61], v[252:253] op_sel_hi:[1,0]
	v_pk_mul_f32 v[62:63], v[62:63], v[252:253] op_sel_hi:[1,0]
	v_pk_mul_f32 v[52:53], v[52:53], v[252:253] op_sel_hi:[1,0]
	v_pk_mul_f32 v[54:55], v[54:55], v[252:253] op_sel_hi:[1,0]
	v_exp_f32_e32 v60, v60
	v_exp_f32_e32 v61, v61
	v_exp_f32_e32 v62, v62
	v_exp_f32_e32 v63, v63
	v_exp_f32_e32 v52, v52
	v_exp_f32_e32 v53, v53
	v_exp_f32_e32 v54, v54
	v_exp_f32_e32 v55, v55
	v_pk_fma_f32 v[60:61], v[60:61], v[254:255], v[254:255] op_sel_hi:[1,0,0]
	v_pk_fma_f32 v[62:63], v[62:63], v[254:255], v[254:255] op_sel_hi:[1,0,0]
	v_pk_fma_f32 v[52:53], v[52:53], v[254:255], v[254:255] op_sel_hi:[1,0,0]
	v_pk_fma_f32 v[54:55], v[54:55], v[254:255], v[254:255] op_sel_hi:[1,0,0]
	v_mul_f32_e32 v238, v60, v61
	v_mul_f32_e32 v242, v62, v63
	v_mul_f32_e32 v246, v52, v53
	v_mul_f32_e32 v250, v54, v55
	v_rcp_f32_e32 v238, v238
	v_rcp_f32_e32 v242, v242
	v_rcp_f32_e32 v246, v246
	v_rcp_f32_e32 v250, v250
	v_pk_mul_f32 v[60:61], v[60:61], v[238:239] op_sel:[1,0] op_sel_hi:[0,0]
	v_pk_mul_f32 v[62:63], v[62:63], v[242:243] op_sel:[1,0] op_sel_hi:[0,0]
	v_pk_mul_f32 v[52:53], v[52:53], v[246:247] op_sel:[1,0] op_sel_hi:[0,0]
	v_pk_mul_f32 v[54:55], v[54:55], v[250:251] op_sel:[1,0] op_sel_hi:[0,0]
	v_pk_mul_f32 v[56:57], v[56:57], v[60:61]
	v_pk_mul_f32 v[58:59], v[58:59], v[62:63]
	v_pk_mul_f32 v[48:49], v[48:49], v[52:53]
	v_pk_mul_f32 v[50:51], v[50:51], v[54:55]
	v_cvt_pk_bf16_f32 v56, v56, v57
	v_cvt_pk_bf16_f32 v57, v58, v59
	v_cvt_pk_bf16_f32 v58, v48, v49
	v_cvt_pk_bf16_f32 v59, v50, v51
	global_store_dwordx4 v235, v[56:59], s[10:11]
	v_add_u32_e32 v234, 0x16000, v235
	v_mul_f32_e32 v252, 0xbfb8aa3b, v240
	v_mul_f32_e32 v254, v240, v240
	v_rcp_f32_e32 v254, v254
	v_pk_mul_f32 v[40:41], v[44:45], v[40:41]
	v_pk_mul_f32 v[42:43], v[46:47], v[42:43]
	v_pk_mul_f32 v[32:33], v[36:37], v[32:33]
	v_pk_mul_f32 v[34:35], v[38:39], v[34:35]
	v_pk_mul_f32 v[44:45], v[44:45], v[252:253] op_sel_hi:[1,0]
	v_pk_mul_f32 v[46:47], v[46:47], v[252:253] op_sel_hi:[1,0]
	v_pk_mul_f32 v[36:37], v[36:37], v[252:253] op_sel_hi:[1,0]
	v_pk_mul_f32 v[38:39], v[38:39], v[252:253] op_sel_hi:[1,0]
	v_exp_f32_e32 v44, v44
	v_exp_f32_e32 v45, v45
	v_exp_f32_e32 v46, v46
	v_exp_f32_e32 v47, v47
	v_exp_f32_e32 v36, v36
	v_exp_f32_e32 v37, v37
	v_exp_f32_e32 v38, v38
	v_exp_f32_e32 v39, v39
	v_pk_fma_f32 v[44:45], v[44:45], v[254:255], v[254:255] op_sel_hi:[1,0,0]
	v_pk_fma_f32 v[46:47], v[46:47], v[254:255], v[254:255] op_sel_hi:[1,0,0]
	v_pk_fma_f32 v[36:37], v[36:37], v[254:255], v[254:255] op_sel_hi:[1,0,0]
	v_pk_fma_f32 v[38:39], v[38:39], v[254:255], v[254:255] op_sel_hi:[1,0,0]
	v_mul_f32_e32 v238, v44, v45
	v_mul_f32_e32 v242, v46, v47
	v_mul_f32_e32 v246, v36, v37
	v_mul_f32_e32 v250, v38, v39
	v_rcp_f32_e32 v238, v238
	v_rcp_f32_e32 v242, v242
	v_rcp_f32_e32 v246, v246
	v_rcp_f32_e32 v250, v250
	v_pk_mul_f32 v[44:45], v[44:45], v[238:239] op_sel:[1,0] op_sel_hi:[0,0]
	v_pk_mul_f32 v[46:47], v[46:47], v[242:243] op_sel:[1,0] op_sel_hi:[0,0]
	v_pk_mul_f32 v[36:37], v[36:37], v[246:247] op_sel:[1,0] op_sel_hi:[0,0]
	v_pk_mul_f32 v[38:39], v[38:39], v[250:251] op_sel:[1,0] op_sel_hi:[0,0]
	v_pk_mul_f32 v[40:41], v[40:41], v[44:45]
	v_pk_mul_f32 v[42:43], v[42:43], v[46:47]
	v_pk_mul_f32 v[32:33], v[32:33], v[36:37]
	v_pk_mul_f32 v[34:35], v[34:35], v[38:39]
	v_cvt_pk_bf16_f32 v40, v40, v41
	v_cvt_pk_bf16_f32 v41, v42, v43
	v_cvt_pk_bf16_f32 v42, v32, v33
	v_cvt_pk_bf16_f32 v43, v34, v35
	global_store_dwordx4 v234, v[40:43], s[10:11]
	v_add_u32_e32 v235, 0x16000, v234
	v_mul_f32_e32 v252, 0xbfb8aa3b, v244
	v_mul_f32_e32 v254, v244, v244
	v_rcp_f32_e32 v254, v254
	v_pk_mul_f32 v[24:25], v[28:29], v[24:25]
	v_pk_mul_f32 v[26:27], v[30:31], v[26:27]
	v_pk_mul_f32 v[16:17], v[20:21], v[16:17]
	v_pk_mul_f32 v[18:19], v[22:23], v[18:19]
	v_pk_mul_f32 v[28:29], v[28:29], v[252:253] op_sel_hi:[1,0]
	v_pk_mul_f32 v[30:31], v[30:31], v[252:253] op_sel_hi:[1,0]
	v_pk_mul_f32 v[20:21], v[20:21], v[252:253] op_sel_hi:[1,0]
	v_pk_mul_f32 v[22:23], v[22:23], v[252:253] op_sel_hi:[1,0]
	v_exp_f32_e32 v28, v28
	v_exp_f32_e32 v29, v29
	v_exp_f32_e32 v30, v30
	v_exp_f32_e32 v31, v31
	v_exp_f32_e32 v20, v20
	v_exp_f32_e32 v21, v21
	v_exp_f32_e32 v22, v22
	v_exp_f32_e32 v23, v23
	v_pk_fma_f32 v[28:29], v[28:29], v[254:255], v[254:255] op_sel_hi:[1,0,0]
	v_pk_fma_f32 v[30:31], v[30:31], v[254:255], v[254:255] op_sel_hi:[1,0,0]
	v_pk_fma_f32 v[20:21], v[20:21], v[254:255], v[254:255] op_sel_hi:[1,0,0]
	v_pk_fma_f32 v[22:23], v[22:23], v[254:255], v[254:255] op_sel_hi:[1,0,0]
	v_mul_f32_e32 v238, v28, v29
	v_mul_f32_e32 v242, v30, v31
	v_mul_f32_e32 v246, v20, v21
	v_mul_f32_e32 v250, v22, v23
	v_rcp_f32_e32 v238, v238
	v_rcp_f32_e32 v242, v242
	v_rcp_f32_e32 v246, v246
	v_rcp_f32_e32 v250, v250
	v_pk_mul_f32 v[28:29], v[28:29], v[238:239] op_sel:[1,0] op_sel_hi:[0,0]
	v_pk_mul_f32 v[30:31], v[30:31], v[242:243] op_sel:[1,0] op_sel_hi:[0,0]
	v_pk_mul_f32 v[20:21], v[20:21], v[246:247] op_sel:[1,0] op_sel_hi:[0,0]
	v_pk_mul_f32 v[22:23], v[22:23], v[250:251] op_sel:[1,0] op_sel_hi:[0,0]
	v_pk_mul_f32 v[24:25], v[24:25], v[28:29]
	v_pk_mul_f32 v[26:27], v[26:27], v[30:31]
	v_pk_mul_f32 v[16:17], v[16:17], v[20:21]
	v_pk_mul_f32 v[18:19], v[18:19], v[22:23]
	v_cvt_pk_bf16_f32 v24, v24, v25
	v_cvt_pk_bf16_f32 v25, v26, v27
	v_cvt_pk_bf16_f32 v26, v16, v17
	v_cvt_pk_bf16_f32 v27, v18, v19
	global_store_dwordx4 v235, v[24:27], s[10:11]
	v_add_u32_e32 v234, 0x16000, v235
	v_mul_f32_e32 v252, 0xbfb8aa3b, v248
	v_mul_f32_e32 v254, v248, v248
	v_rcp_f32_e32 v254, v254
	v_pk_mul_f32 v[8:9], v[12:13], v[8:9]
	v_pk_mul_f32 v[10:11], v[14:15], v[10:11]
	v_pk_mul_f32 v[0:1], v[4:5], v[0:1]
	v_pk_mul_f32 v[2:3], v[6:7], v[2:3]
	v_pk_mul_f32 v[12:13], v[12:13], v[252:253] op_sel_hi:[1,0]
	v_pk_mul_f32 v[14:15], v[14:15], v[252:253] op_sel_hi:[1,0]
	v_pk_mul_f32 v[4:5], v[4:5], v[252:253] op_sel_hi:[1,0]
	v_pk_mul_f32 v[6:7], v[6:7], v[252:253] op_sel_hi:[1,0]
	v_exp_f32_e32 v12, v12
	v_exp_f32_e32 v13, v13
	v_exp_f32_e32 v14, v14
	v_exp_f32_e32 v15, v15
	v_exp_f32_e32 v4, v4
	v_exp_f32_e32 v5, v5
	v_exp_f32_e32 v6, v6
	v_exp_f32_e32 v7, v7
	v_pk_fma_f32 v[12:13], v[12:13], v[254:255], v[254:255] op_sel_hi:[1,0,0]
	v_pk_fma_f32 v[14:15], v[14:15], v[254:255], v[254:255] op_sel_hi:[1,0,0]
	v_pk_fma_f32 v[4:5], v[4:5], v[254:255], v[254:255] op_sel_hi:[1,0,0]
	v_pk_fma_f32 v[6:7], v[6:7], v[254:255], v[254:255] op_sel_hi:[1,0,0]
	v_mul_f32_e32 v238, v12, v13
	v_mul_f32_e32 v242, v14, v15
	v_mul_f32_e32 v246, v4, v5
	v_mul_f32_e32 v250, v6, v7
	v_rcp_f32_e32 v238, v238
	v_rcp_f32_e32 v242, v242
	v_rcp_f32_e32 v246, v246
	v_rcp_f32_e32 v250, v250
	v_pk_mul_f32 v[12:13], v[12:13], v[238:239] op_sel:[1,0] op_sel_hi:[0,0]
	v_pk_mul_f32 v[14:15], v[14:15], v[242:243] op_sel:[1,0] op_sel_hi:[0,0]
	v_pk_mul_f32 v[4:5], v[4:5], v[246:247] op_sel:[1,0] op_sel_hi:[0,0]
	v_pk_mul_f32 v[6:7], v[6:7], v[250:251] op_sel:[1,0] op_sel_hi:[0,0]
	v_pk_mul_f32 v[8:9], v[8:9], v[12:13]
	v_pk_mul_f32 v[10:11], v[10:11], v[14:15]
	v_pk_mul_f32 v[0:1], v[0:1], v[4:5]
	v_pk_mul_f32 v[2:3], v[2:3], v[6:7]
	v_cvt_pk_bf16_f32 v8, v8, v9
	v_cvt_pk_bf16_f32 v9, v10, v11
	v_cvt_pk_bf16_f32 v10, v0, v1
	v_cvt_pk_bf16_f32 v11, v2, v3
	global_store_dwordx4 v234, v[8:11], s[10:11]
	s_andn2_b64 vcc, exec, s[6:7]
	s_mov_b64 s[6:7], -1
	s_cbranch_vccnz .LBB0_1093
	s_andn2_b64 vcc, exec, s[8:9]
	s_cbranch_vccnz .LBB0_1092
	s_barrier
	s_branch .LBB0_1092
